# hand-written HGRN2 chunkwise unit: MFMA part of chunk c and exp-prep of chunk c+1 in one barrier interval, wave halves run them in opposite order
# speedup vs baseline: 1.0092x; 1.0034x over previous
.LBB0_583:
	s_and_b64 vcc, exec, s[0:1]
	s_cbranch_vccz .LBB0_747
	v_readlane_b32 s0, v244, 0
	v_readlane_b32 s1, v244, 1
	s_mov_b64 s[6:7], s[46:47]
	v_mov_b32_e32 v58, v194
	s_andn2_b64 vcc, exec, s[0:1]
	s_cbranch_vccnz .LBB0_610
	s_mov_b32 s29, 0x428c0000
	s_and_b32 s0, s2, 3
	s_lshr_b32 s1, s2, 2
	s_mul_i32 s16, s1, 43
	s_lshr_b32 s16, s16, 8
	s_mul_i32 s17, s16, 6
	s_sub_u32 s17, s1, s17
	s_lshl_b32 s16, s16, 12
	s_lshl_b32 s0, s0, 10
	s_add_u32 s16, s16, s0
	s_lshl_b32 s17, s17, 7
	s_mul_i32 s0, s16, 0x300
	s_add_u32 s0, s0, s17
	s_lshl_b32 s1, s0, 2
	s_add_u32 s4, s6, s1
	s_addc_u32 s5, s7, 0
	s_add_u32 s4, s4, 0x16200000
	s_addc_u32 s5, s5, 0
	s_lshl_b32 s1, s0, 1
	s_add_u32 s8, s6, s1
	s_addc_u32 s9, s7, 0
	s_add_u32 s10, s8, 0x10200000
	s_addc_u32 s11, s9, 0
	s_add_u32 s8, s8, 0xd200000
	s_addc_u32 s9, s9, 0
	s_add_u32 s12, s44, s1
	s_addc_u32 s13, s45, 0
	s_lshl_b32 s0, s16, 10
	s_add_u32 s0, s0, s17
	s_lshl_b32 s0, s0, 1
	s_add_u32 s14, s6, s0
	s_addc_u32 s15, s7, 0
	s_add_u32 s14, s14, 0x8200000
	s_addc_u32 s15, s15, 0
	v_and_b32_e32 v26, 0x7f, v194
	v_lshrrev_b32_e32 v27, 7, v194
	v_lshlrev_b32_e32 v0, 2, v26
	v_lshl_add_u32 v1, v27, 9, v0
	v_add_u32_e32 v1, 0xd800, v1
	v_mul_u32_u24_e32 v2, 0x880, v27
	v_lshl_add_u32 v2, v26, 1, v2
	v_mul_u32_u24_e32 v4, 0x50, v26
	v_lshl_add_u32 v4, v27, 4, v4
	v_mul_u32_u24_e32 v200, 0x6000, v27
	v_add_u32_e32 v14, v200, v0
	v_add_u32_e32 v15, 0x1800, v14
	v_add_u32_e32 v16, 0x3000, v14
	v_add_u32_e32 v17, 0x4800, v14
	v_mul_u32_u24_e32 v200, 0x3000, v27
	v_lshl_add_u32 v18, v26, 1, v200
	v_add_u32_e32 v19, 0x1200, v18
	v_add_u32_e32 v20, 0x2400, v18
	v_cmp_lt_u32_e32 vcc, 0, v27
	s_nop 1
	v_cndmask_b32_e64 v21, 0, 1.0, vcc
	v_cmp_lt_u32_e32 vcc, 1, v27
	s_nop 1
	v_cndmask_b32_e64 v22, 0, 1.0, vcc
	v_cmp_lt_u32_e32 vcc, 2, v27
	s_nop 1
	v_cndmask_b32_e64 v23, 0, 1.0, vcc
	v_mov_b32_e32 v24, 0
	v_and_b32_e32 v26, 15, v197
	v_lshrrev_b32_e32 v27, 4, v197
	v_readfirstlane_b32 s18, v194
	s_nop 3
	s_lshr_b32 s18, s18, 6
	v_mul_u32_u24_e32 v5, 0x110, v26
	v_lshl_add_u32 v6, v27, 3, v5
	v_lshl_add_u32 v5, v27, 4, v5
	v_mul_u32_u24_e32 v9, 0x50, v26
	v_lshl_add_u32 v9, v27, 4, v9
	s_mul_i32 s19, s18, 0x500
	v_add_u32_e32 v8, s19, v9
	v_mul_u32_u24_e32 v7, 0x50, v26
	v_lshl_add_u32 v7, v27, 3, v7
	v_add_u32_e32 v7, s19, v7
	v_lshlrev_b32_e32 v10, 4, v27
	v_mul_u32_u24_e32 v11, 0x840, v27
	v_lshl_add_u32 v11, v26, 2, v11
	s_lshl_b32 s19, s18, 6
	v_add_u32_e32 v11, s19, v11
	v_add_u32_e32 v11, 0x9600, v11
	v_lshrrev_b32_e32 v200, 4, v194
	v_and_b32_e32 v201, 15, v194
	v_mul_u32_u24_e32 v12, 0x210, v200
	v_lshl_add_u32 v12, v201, 5, v12
	v_add_u32_e32 v12, 0x9600, v12
	v_lshlrev_b32_e32 v13, 11, v200
	v_lshl_add_u32 v13, v201, 4, v13
	v_lshlrev_b32_e32 v25, 11, v27
	v_lshl_add_u32 v25, v26, 2, v25
	v_add_u32_e32 v25, s19, v25
	v_lshlrev_b32_e32 v200, 2, v27
	v_add_u32_e32 v201, 0, v200
	v_cmp_le_u32_e64 s[40:41], v201, v26
	v_add_u32_e32 v201, 1, v200
	v_cmp_le_u32_e64 s[42:43], v201, v26
	v_add_u32_e32 v201, 2, v200
	v_cmp_le_u32_e64 s[44:45], v201, v26
	v_add_u32_e32 v201, 3, v200
	v_cmp_le_u32_e64 s[46:47], v201, v26
	v_mov_b32_e32 v92, 0
	v_mov_b32_e32 v93, 0
	v_mov_b32_e32 v94, 0
	v_mov_b32_e32 v95, 0
	v_mov_b32_e32 v96, 0
	v_mov_b32_e32 v97, 0
	v_mov_b32_e32 v98, 0
	v_mov_b32_e32 v99, 0
	v_mov_b32_e32 v100, 0
	v_mov_b32_e32 v101, 0
	v_mov_b32_e32 v102, 0
	v_mov_b32_e32 v103, 0
	v_mov_b32_e32 v104, 0
	v_mov_b32_e32 v105, 0
	v_mov_b32_e32 v106, 0
	v_mov_b32_e32 v107, 0
	v_mov_b32_e32 v108, 0
	v_mov_b32_e32 v109, 0
	v_mov_b32_e32 v110, 0
	v_mov_b32_e32 v111, 0
	v_mov_b32_e32 v112, 0
	v_mov_b32_e32 v113, 0
	v_mov_b32_e32 v114, 0
	v_mov_b32_e32 v115, 0
	v_mov_b32_e32 v116, 0
	v_mov_b32_e32 v117, 0
	v_mov_b32_e32 v118, 0
	v_mov_b32_e32 v119, 0
	v_mov_b32_e32 v120, 0
	v_mov_b32_e32 v121, 0
	v_mov_b32_e32 v122, 0
	v_mov_b32_e32 v123, 0
	v_mov_b32_e32 v26, v0
	global_load_dword v28, v14, s[4:5]
	global_load_dword v29, v14, s[4:5] offset:3072
	global_load_dword v30, v15, s[4:5]
	global_load_dword v31, v15, s[4:5] offset:3072
	global_load_dword v32, v16, s[4:5]
	global_load_dword v33, v16, s[4:5] offset:3072
	global_load_dword v34, v17, s[4:5]
	global_load_dword v35, v17, s[4:5] offset:3072
	global_load_ushort v44, v18, s[8:9]
	global_load_ushort v45, v18, s[8:9] offset:1536
	global_load_ushort v46, v18, s[8:9] offset:3072
	global_load_ushort v47, v19, s[8:9]
	global_load_ushort v48, v19, s[8:9] offset:1536
	global_load_ushort v49, v19, s[8:9] offset:3072
	global_load_ushort v50, v20, s[8:9]
	global_load_ushort v51, v20, s[8:9] offset:1536
	global_load_ushort v52, v18, s[10:11]
	global_load_ushort v53, v18, s[10:11] offset:1536
	global_load_ushort v54, v18, s[10:11] offset:3072
	global_load_ushort v55, v19, s[10:11]
	global_load_ushort v56, v19, s[10:11] offset:1536
	global_load_ushort v57, v19, s[10:11] offset:3072
	global_load_ushort v58, v20, s[10:11]
	global_load_ushort v59, v20, s[10:11] offset:1536
	s_add_u32 s4, s4, 0x18000
	s_addc_u32 s5, s5, 0
	s_add_u32 s8, s8, 0xc000
	s_addc_u32 s9, s9, 0
	s_add_u32 s10, s10, 0xc000
	s_addc_u32 s11, s11, 0
	global_load_dword v60, v14, s[4:5]
	global_load_dword v61, v14, s[4:5] offset:3072
	global_load_dword v62, v15, s[4:5]
	global_load_dword v63, v15, s[4:5] offset:3072
	global_load_dword v64, v16, s[4:5]
	global_load_dword v65, v16, s[4:5] offset:3072
	global_load_dword v66, v17, s[4:5]
	global_load_dword v67, v17, s[4:5] offset:3072
	global_load_ushort v76, v18, s[8:9]
	global_load_ushort v77, v18, s[8:9] offset:1536
	global_load_ushort v78, v18, s[8:9] offset:3072
	global_load_ushort v79, v19, s[8:9]
	global_load_ushort v80, v19, s[8:9] offset:1536
	global_load_ushort v81, v19, s[8:9] offset:3072
	global_load_ushort v82, v20, s[8:9]
	global_load_ushort v83, v20, s[8:9] offset:1536
	global_load_ushort v84, v18, s[10:11]
	global_load_ushort v85, v18, s[10:11] offset:1536
	global_load_ushort v86, v18, s[10:11] offset:3072
	global_load_ushort v87, v19, s[10:11]
	global_load_ushort v88, v19, s[10:11] offset:1536
	global_load_ushort v89, v19, s[10:11] offset:3072
	global_load_ushort v90, v20, s[10:11]
	global_load_ushort v91, v20, s[10:11] offset:1536
	s_add_u32 s4, s4, 0x18000
	s_addc_u32 s5, s5, 0
	s_add_u32 s8, s8, 0xc000
	s_addc_u32 s9, s9, 0
	s_add_u32 s10, s10, 0xc000
	s_addc_u32 s11, s11, 0
	s_waitcnt vmcnt(24)
	v_mov_b32_e32 v36, v28
	v_add_f32_e32 v37, v36, v29
	v_add_f32_e32 v38, v37, v30
	v_add_f32_e32 v39, v38, v31
	v_add_f32_e32 v40, v39, v32
	v_add_f32_e32 v41, v40, v33
	v_add_f32_e32 v42, v41, v34
	v_add_f32_e32 v43, v42, v35
	ds_write_b32 v1, v43
	s_waitcnt lgkmcnt(0)
	s_barrier
	ds_read_b32 v200, v0 offset:55296
	ds_read_b32 v201, v0 offset:55808
	ds_read_b32 v202, v0 offset:56320
	ds_read_b32 v203, v0 offset:56832
	v_lshl_or_b32 v220, v53, 16, v52
	v_lshl_or_b32 v221, v55, 16, v54
	v_lshl_or_b32 v222, v57, 16, v56
	v_lshl_or_b32 v223, v59, 16, v58
	ds_write_b128 v4, v[220:223] offset:27648
	s_waitcnt lgkmcnt(1)
	v_mul_f32_e32 v204, v21, v200
	v_fmac_f32_e32 v204, v22, v201
	v_fmac_f32_e32 v204, v23, v202
	v_add_f32_e32 v205, v200, v201
	v_add_f32_e32 v205, v205, v202
	v_add_f32_e32 v205, v205, v203
	v_add_f32_e32 v218, v204, v36
	v_mul_f32_e32 v207, 0x3fb8aa3b, v28
	v_exp_f32_e32 v207, v207
	v_lshlrev_b32_e32 v209, 16, v44
	v_sub_f32_e32 v208, 1.0, v207
	v_mul_f32_e32 v207, 0x3fb8aa3b, v218
	v_exp_f32_e32 v207, v207
	v_add_f32_e32 v206, v218, v24
	v_mul_f32_e32 v224, v209, v207
	v_mul_f32_e32 v206, 0x3fb8aa3b, v206
	v_exp_f32_e32 v206, v206
	v_sub_f32_e32 v207, v205, v218
	v_mul_f32_e32 v28, v209, v206
	v_mul_f32_e32 v207, 0x3fb8aa3b, v207
	v_exp_f32_e32 v207, v207
	v_min_f32_e64 v206, -v218, s29
	v_mul_f32_e32 v210, v208, v207
	v_mul_f32_e32 v206, 0x3fb8aa3b, v206
	v_exp_f32_e32 v206, v206
	s_nop 0
	v_mul_f32_e32 v232, v208, v206
	v_add_f32_e32 v218, v204, v37
	v_mul_f32_e32 v207, 0x3fb8aa3b, v29
	v_exp_f32_e32 v207, v207
	v_lshlrev_b32_e32 v209, 16, v45
	v_sub_f32_e32 v208, 1.0, v207
	v_mul_f32_e32 v207, 0x3fb8aa3b, v218
	v_exp_f32_e32 v207, v207
	v_add_f32_e32 v206, v218, v24
	v_mul_f32_e32 v225, v209, v207
	v_mul_f32_e32 v206, 0x3fb8aa3b, v206
	v_exp_f32_e32 v206, v206
	v_sub_f32_e32 v207, v205, v218
	v_mul_f32_e32 v29, v209, v206
	v_mul_f32_e32 v207, 0x3fb8aa3b, v207
	v_exp_f32_e32 v207, v207
	v_min_f32_e64 v206, -v218, s29
	v_mul_f32_e32 v211, v208, v207
	v_mul_f32_e32 v206, 0x3fb8aa3b, v206
	v_exp_f32_e32 v206, v206
	s_nop 0
	v_mul_f32_e32 v233, v208, v206
	v_add_f32_e32 v218, v204, v38
	v_mul_f32_e32 v207, 0x3fb8aa3b, v30
	v_exp_f32_e32 v207, v207
	v_lshlrev_b32_e32 v209, 16, v46
	v_sub_f32_e32 v208, 1.0, v207
	v_mul_f32_e32 v207, 0x3fb8aa3b, v218
	v_exp_f32_e32 v207, v207
	v_add_f32_e32 v206, v218, v24
	v_mul_f32_e32 v226, v209, v207
	v_mul_f32_e32 v206, 0x3fb8aa3b, v206
	v_exp_f32_e32 v206, v206
	v_sub_f32_e32 v207, v205, v218
	v_mul_f32_e32 v30, v209, v206
	v_mul_f32_e32 v207, 0x3fb8aa3b, v207
	v_exp_f32_e32 v207, v207
	v_min_f32_e64 v206, -v218, s29
	v_mul_f32_e32 v212, v208, v207
	v_mul_f32_e32 v206, 0x3fb8aa3b, v206
	v_exp_f32_e32 v206, v206
	s_nop 0
	v_mul_f32_e32 v234, v208, v206
	v_add_f32_e32 v218, v204, v39
	v_mul_f32_e32 v207, 0x3fb8aa3b, v31
	v_exp_f32_e32 v207, v207
	v_lshlrev_b32_e32 v209, 16, v47
	v_sub_f32_e32 v208, 1.0, v207
	v_mul_f32_e32 v207, 0x3fb8aa3b, v218
	v_exp_f32_e32 v207, v207
	v_add_f32_e32 v206, v218, v24
	v_mul_f32_e32 v227, v209, v207
	v_mul_f32_e32 v206, 0x3fb8aa3b, v206
	v_exp_f32_e32 v206, v206
	v_sub_f32_e32 v207, v205, v218
	v_mul_f32_e32 v31, v209, v206
	v_mul_f32_e32 v207, 0x3fb8aa3b, v207
	v_exp_f32_e32 v207, v207
	v_min_f32_e64 v206, -v218, s29
	v_mul_f32_e32 v213, v208, v207
	v_mul_f32_e32 v206, 0x3fb8aa3b, v206
	v_exp_f32_e32 v206, v206
	s_nop 0
	v_mul_f32_e32 v235, v208, v206
	v_add_f32_e32 v218, v204, v40
	v_mul_f32_e32 v207, 0x3fb8aa3b, v32
	v_exp_f32_e32 v207, v207
	v_lshlrev_b32_e32 v209, 16, v48
	v_sub_f32_e32 v208, 1.0, v207
	v_mul_f32_e32 v207, 0x3fb8aa3b, v218
	v_exp_f32_e32 v207, v207
	v_add_f32_e32 v206, v218, v24
	v_mul_f32_e32 v228, v209, v207
	v_mul_f32_e32 v206, 0x3fb8aa3b, v206
	v_exp_f32_e32 v206, v206
	v_sub_f32_e32 v207, v205, v218
	v_mul_f32_e32 v32, v209, v206
	v_mul_f32_e32 v207, 0x3fb8aa3b, v207
	v_exp_f32_e32 v207, v207
	v_min_f32_e64 v206, -v218, s29
	v_mul_f32_e32 v214, v208, v207
	v_mul_f32_e32 v206, 0x3fb8aa3b, v206
	v_exp_f32_e32 v206, v206
	s_nop 0
	v_mul_f32_e32 v236, v208, v206
	v_add_f32_e32 v218, v204, v41
	v_mul_f32_e32 v207, 0x3fb8aa3b, v33
	v_exp_f32_e32 v207, v207
	v_lshlrev_b32_e32 v209, 16, v49
	v_sub_f32_e32 v208, 1.0, v207
	v_mul_f32_e32 v207, 0x3fb8aa3b, v218
	v_exp_f32_e32 v207, v207
	v_add_f32_e32 v206, v218, v24
	v_mul_f32_e32 v229, v209, v207
	v_mul_f32_e32 v206, 0x3fb8aa3b, v206
	v_exp_f32_e32 v206, v206
	v_sub_f32_e32 v207, v205, v218
	v_mul_f32_e32 v33, v209, v206
	v_mul_f32_e32 v207, 0x3fb8aa3b, v207
	v_exp_f32_e32 v207, v207
	v_min_f32_e64 v206, -v218, s29
	v_mul_f32_e32 v215, v208, v207
	v_mul_f32_e32 v206, 0x3fb8aa3b, v206
	v_exp_f32_e32 v206, v206
	s_nop 0
	v_mul_f32_e32 v237, v208, v206
	v_add_f32_e32 v218, v204, v42
	v_mul_f32_e32 v207, 0x3fb8aa3b, v34
	v_exp_f32_e32 v207, v207
	v_lshlrev_b32_e32 v209, 16, v50
	v_sub_f32_e32 v208, 1.0, v207
	v_mul_f32_e32 v207, 0x3fb8aa3b, v218
	v_exp_f32_e32 v207, v207
	v_add_f32_e32 v206, v218, v24
	v_mul_f32_e32 v230, v209, v207
	v_mul_f32_e32 v206, 0x3fb8aa3b, v206
	v_exp_f32_e32 v206, v206
	v_sub_f32_e32 v207, v205, v218
	v_mul_f32_e32 v34, v209, v206
	v_mul_f32_e32 v207, 0x3fb8aa3b, v207
	v_exp_f32_e32 v207, v207
	v_min_f32_e64 v206, -v218, s29
	v_mul_f32_e32 v216, v208, v207
	v_mul_f32_e32 v206, 0x3fb8aa3b, v206
	v_exp_f32_e32 v206, v206
	s_nop 0
	v_mul_f32_e32 v238, v208, v206
	v_add_f32_e32 v218, v204, v43
	v_mul_f32_e32 v207, 0x3fb8aa3b, v35
	v_exp_f32_e32 v207, v207
	v_lshlrev_b32_e32 v209, 16, v51
	v_sub_f32_e32 v208, 1.0, v207
	v_mul_f32_e32 v207, 0x3fb8aa3b, v218
	v_exp_f32_e32 v207, v207
	v_add_f32_e32 v206, v218, v24
	v_mul_f32_e32 v231, v209, v207
	v_mul_f32_e32 v206, 0x3fb8aa3b, v206
	v_exp_f32_e32 v206, v206
	v_sub_f32_e32 v207, v205, v218
	v_mul_f32_e32 v35, v209, v206
	v_mul_f32_e32 v207, 0x3fb8aa3b, v207
	v_exp_f32_e32 v207, v207
	v_min_f32_e64 v206, -v218, s29
	v_mul_f32_e32 v217, v208, v207
	v_mul_f32_e32 v206, 0x3fb8aa3b, v206
	v_exp_f32_e32 v206, v206
	s_nop 0
	v_mul_f32_e32 v239, v208, v206
	v_cvt_pk_bf16_f32 v224, v224, v225
	ds_write_b16 v2, v224
	ds_write_b16_d16_hi v2, v224 offset:272
	v_cvt_pk_bf16_f32 v232, v232, v233
	ds_write_b16 v2, v232 offset:8704
	ds_write_b16_d16_hi v2, v232 offset:8976
	v_cvt_pk_bf16_f32 v226, v226, v227
	ds_write_b16 v2, v226 offset:544
	ds_write_b16_d16_hi v2, v226 offset:816
	v_cvt_pk_bf16_f32 v234, v234, v235
	ds_write_b16 v2, v234 offset:9248
	ds_write_b16_d16_hi v2, v234 offset:9520
	v_cvt_pk_bf16_f32 v228, v228, v229
	ds_write_b16 v2, v228 offset:1088
	ds_write_b16_d16_hi v2, v228 offset:1360
	v_cvt_pk_bf16_f32 v236, v236, v237
	ds_write_b16 v2, v236 offset:9792
	ds_write_b16_d16_hi v2, v236 offset:10064
	v_cvt_pk_bf16_f32 v230, v230, v231
	ds_write_b16 v2, v230 offset:1632
	ds_write_b16_d16_hi v2, v230 offset:1904
	v_cvt_pk_bf16_f32 v238, v238, v239
	ds_write_b16 v2, v238 offset:10336
	ds_write_b16_d16_hi v2, v238 offset:10608
	v_cvt_pk_bf16_f32 v210, v210, v211
	v_cvt_pk_bf16_f32 v211, v212, v213
	v_cvt_pk_bf16_f32 v212, v214, v215
	v_cvt_pk_bf16_f32 v213, v216, v217
	ds_write_b128 v4, v[210:213] offset:17408
	v_cvt_pk_bf16_f32 v28, v28, v29
	v_cvt_pk_bf16_f32 v30, v30, v31
	v_cvt_pk_bf16_f32 v32, v32, v33
	v_cvt_pk_bf16_f32 v34, v34, v35
	global_store_short v18, v28, s[12:13]
	global_store_short_d16_hi v18, v28, s[12:13] offset:1536
	global_store_short v18, v30, s[12:13] offset:3072
	global_store_short_d16_hi v19, v30, s[12:13]
	global_store_short v19, v32, s[12:13] offset:1536
	global_store_short_d16_hi v19, v32, s[12:13] offset:3072
	global_store_short v20, v34, s[12:13]
	global_store_short_d16_hi v20, v34, s[12:13] offset:1536
	s_add_u32 s12, s12, 0xc000
	s_addc_u32 s13, s13, 0
	s_cmp_gt_u32 s18, 1
	s_cbranch_scc1 .Lhg_w01_1
	v_mul_f32_e32 v207, 0x3fb8aa3b, v205
	v_exp_f32_e32 v207, v207
	s_nop 0
	ds_write_b32 v26, v207 offset:37888
.Lhg_w01_1:
	v_add_f32_e32 v24, v24, v205
	s_waitcnt lgkmcnt(0)
	s_barrier
	v_xor_b32_e32 v2, 0x10000, v2
	v_xor_b32_e32 v4, 0x10000, v4
	v_xor_b32_e32 v26, 0x10000, v26
	s_waitcnt vmcnt(0)
	s_mov_b32 s28, 0
.Lhg_loop:
	v_mov_b32_e32 v68, v60
	v_add_f32_e32 v69, v68, v61
	v_add_f32_e32 v70, v69, v62
	v_add_f32_e32 v71, v70, v63
	v_add_f32_e32 v72, v71, v64
	v_add_f32_e32 v73, v72, v65
	v_add_f32_e32 v74, v73, v66
	v_add_f32_e32 v75, v74, v67
	ds_write_b32 v1, v75
	s_waitcnt lgkmcnt(0)
	s_barrier
	s_cmp_gt_u32 s28, 29
	s_cbranch_scc1 .Lhg_noload_2
	global_load_dword v28, v14, s[4:5]
	global_load_dword v29, v14, s[4:5] offset:3072
	global_load_dword v30, v15, s[4:5]
	global_load_dword v31, v15, s[4:5] offset:3072
	global_load_dword v32, v16, s[4:5]
	global_load_dword v33, v16, s[4:5] offset:3072
	global_load_dword v34, v17, s[4:5]
	global_load_dword v35, v17, s[4:5] offset:3072
	global_load_ushort v44, v18, s[8:9]
	global_load_ushort v45, v18, s[8:9] offset:1536
	global_load_ushort v46, v18, s[8:9] offset:3072
	global_load_ushort v47, v19, s[8:9]
	global_load_ushort v48, v19, s[8:9] offset:1536
	global_load_ushort v49, v19, s[8:9] offset:3072
	global_load_ushort v50, v20, s[8:9]
	global_load_ushort v51, v20, s[8:9] offset:1536
	global_load_ushort v52, v18, s[10:11]
	global_load_ushort v53, v18, s[10:11] offset:1536
	global_load_ushort v54, v18, s[10:11] offset:3072
	global_load_ushort v55, v19, s[10:11]
	global_load_ushort v56, v19, s[10:11] offset:1536
	global_load_ushort v57, v19, s[10:11] offset:3072
	global_load_ushort v58, v20, s[10:11]
	global_load_ushort v59, v20, s[10:11] offset:1536
	s_add_u32 s4, s4, 0x18000
	s_addc_u32 s5, s5, 0
	s_add_u32 s8, s8, 0xc000
	s_addc_u32 s9, s9, 0
	s_add_u32 s10, s10, 0xc000
	s_addc_u32 s11, s11, 0
.Lhg_noload_2:
	s_cmp_gt_u32 s18, 3
	s_cbranch_scc1 .Lhg_bfirst_3
	ds_read_b128 v[144:147], v5 offset:8704
	ds_read_b128 v[148:151], v5 offset:13056
	ds_read_b128 v[152:155], v5 offset:0
	ds_read_b128 v[172:175], v5 offset:4352
	ds_read_b128 v[176:179], v5 offset:8768
	ds_read_b128 v[180:183], v5 offset:13120
	ds_read_b128 v[184:187], v5 offset:64
	ds_read_b128 v[188:191], v5 offset:4416
	s_waitcnt lgkmcnt(4)
	v_mfma_f32_16x16x32_bf16 v[124:127], v[144:147], v[152:155], 0
	v_mfma_f32_16x16x32_bf16 v[128:131], v[144:147], v[172:175], 0
	v_mfma_f32_16x16x32_bf16 v[132:135], v[148:151], v[172:175], 0
	ds_read_b128 v[144:147], v5 offset:8832
	ds_read_b128 v[148:151], v5 offset:13184
	ds_read_b128 v[152:155], v5 offset:128
	ds_read_b128 v[172:175], v5 offset:4480
	s_waitcnt lgkmcnt(4)
	v_mfma_f32_16x16x32_bf16 v[124:127], v[176:179], v[184:187], v[124:127]
	v_mfma_f32_16x16x32_bf16 v[128:131], v[176:179], v[188:191], v[128:131]
	v_mfma_f32_16x16x32_bf16 v[132:135], v[180:183], v[188:191], v[132:135]
	ds_read_b128 v[176:179], v5 offset:8896
	ds_read_b128 v[180:183], v5 offset:13248
	ds_read_b128 v[184:187], v5 offset:192
	ds_read_b128 v[188:191], v5 offset:4544
	s_waitcnt lgkmcnt(4)
	v_mfma_f32_16x16x32_bf16 v[124:127], v[144:147], v[152:155], v[124:127]
	v_mfma_f32_16x16x32_bf16 v[128:131], v[144:147], v[172:175], v[128:131]
	v_mfma_f32_16x16x32_bf16 v[132:135], v[148:151], v[172:175], v[132:135]
	s_waitcnt lgkmcnt(0)
	v_mfma_f32_16x16x32_bf16 v[124:127], v[176:179], v[184:187], v[124:127]
	v_mfma_f32_16x16x32_bf16 v[128:131], v[176:179], v[188:191], v[128:131]
	v_mfma_f32_16x16x32_bf16 v[132:135], v[180:183], v[188:191], v[132:135]
	ds_read_b64 v[204:205], v6
	ds_read_b64 v[206:207], v6 offset:32
	ds_read_b64 v[208:209], v6 offset:4352
	ds_read_b64 v[210:211], v6 offset:4384
	v_cvt_pk_bf16_f32 v200, v92, v93
	v_cvt_pk_bf16_f32 v201, v94, v95
	v_cvt_pk_bf16_f32 v202, v96, v97
	v_cvt_pk_bf16_f32 v203, v98, v99
	s_waitcnt lgkmcnt(0)
	s_nop 1
	v_mfma_f32_16x16x32_bf16 v[136:139], v[204:207], v[200:203], 0
	v_mfma_f32_16x16x32_bf16 v[140:143], v[208:211], v[200:203], 0
	ds_read_b64 v[204:205], v6 offset:64
	ds_read_b64 v[206:207], v6 offset:96
	ds_read_b64 v[208:209], v6 offset:4416
	ds_read_b64 v[210:211], v6 offset:4448
	v_cvt_pk_bf16_f32 v200, v100, v101
	v_cvt_pk_bf16_f32 v201, v102, v103
	v_cvt_pk_bf16_f32 v202, v104, v105
	v_cvt_pk_bf16_f32 v203, v106, v107
	s_waitcnt lgkmcnt(0)
	s_nop 1
	v_mfma_f32_16x16x32_bf16 v[136:139], v[204:207], v[200:203], v[136:139]
	v_mfma_f32_16x16x32_bf16 v[140:143], v[208:211], v[200:203], v[140:143]
	ds_read_b64 v[204:205], v6 offset:128
	ds_read_b64 v[206:207], v6 offset:160
	ds_read_b64 v[208:209], v6 offset:4480
	ds_read_b64 v[210:211], v6 offset:4512
	v_cvt_pk_bf16_f32 v200, v108, v109
	v_cvt_pk_bf16_f32 v201, v110, v111
	v_cvt_pk_bf16_f32 v202, v112, v113
	v_cvt_pk_bf16_f32 v203, v114, v115
	s_waitcnt lgkmcnt(0)
	s_nop 1
	v_mfma_f32_16x16x32_bf16 v[136:139], v[204:207], v[200:203], v[136:139]
	v_mfma_f32_16x16x32_bf16 v[140:143], v[208:211], v[200:203], v[140:143]
	ds_read_b64 v[204:205], v6 offset:192
	ds_read_b64 v[206:207], v6 offset:224
	ds_read_b64 v[208:209], v6 offset:4544
	ds_read_b64 v[210:211], v6 offset:4576
	v_cvt_pk_bf16_f32 v200, v116, v117
	v_cvt_pk_bf16_f32 v201, v118, v119
	v_cvt_pk_bf16_f32 v202, v120, v121
	v_cvt_pk_bf16_f32 v203, v122, v123
	s_waitcnt lgkmcnt(0)
	s_nop 1
	v_mfma_f32_16x16x32_bf16 v[136:139], v[204:207], v[200:203], v[136:139]
	v_mfma_f32_16x16x32_bf16 v[140:143], v[208:211], v[200:203], v[140:143]
	ds_read_b64 v[212:213], v7 offset:27648
	ds_read_b64 v[214:215], v7 offset:27680
	ds_read_b128 v[216:219], v8 offset:27648
	v_cndmask_b32_e64 v124, 0, v124, s[40:41]
	v_cndmask_b32_e64 v132, 0, v132, s[40:41]
	v_cndmask_b32_e64 v125, 0, v125, s[42:43]
	v_cndmask_b32_e64 v133, 0, v133, s[42:43]
	v_cndmask_b32_e64 v126, 0, v126, s[44:45]
	v_cndmask_b32_e64 v134, 0, v134, s[44:45]
	v_cndmask_b32_e64 v127, 0, v127, s[46:47]
	v_cndmask_b32_e64 v135, 0, v135, s[46:47]
	v_cvt_pk_bf16_f32 v124, v124, v125
	v_cvt_pk_bf16_f32 v125, v126, v127
	v_mov_b32_e32 v126, 0
	v_mov_b32_e32 v127, 0
	v_cvt_pk_bf16_f32 v128, v128, v129
	v_cvt_pk_bf16_f32 v129, v130, v131
	v_cvt_pk_bf16_f32 v130, v132, v133
	v_cvt_pk_bf16_f32 v131, v134, v135
	s_waitcnt lgkmcnt(0)
	s_nop 1
	v_mfma_f32_16x16x32_bf16 v[136:139], v[124:127], v[212:215], v[136:139]
	v_mfma_f32_16x16x32_bf16 v[140:143], v[128:131], v[212:215], v[140:143]
	ds_read_b128 v[220:223], v9 offset:17408
	ds_read_b128 v[228:231], v10 offset:37888
	ds_read_b128 v[224:227], v9 offset:18688
	ds_read_b128 v[232:235], v10 offset:37952
	s_waitcnt lgkmcnt(2)
	v_pk_mul_f32 v[92:93], v[92:93], v[228:229]
	v_pk_mul_f32 v[94:95], v[94:95], v[230:231]
	s_nop 1
	v_mfma_f32_16x16x32_bf16 v[92:95], v[220:223], v[216:219], v[92:95]
	ds_read_b128 v[220:223], v9 offset:19968
	ds_read_b128 v[228:231], v10 offset:38016
	s_waitcnt lgkmcnt(2)
	v_pk_mul_f32 v[96:97], v[96:97], v[232:233]
	v_pk_mul_f32 v[98:99], v[98:99], v[234:235]
	s_nop 1
	v_mfma_f32_16x16x32_bf16 v[96:99], v[224:227], v[216:219], v[96:99]
	ds_read_b128 v[224:227], v9 offset:21248
	ds_read_b128 v[232:235], v10 offset:38080
	s_waitcnt lgkmcnt(2)
	v_pk_mul_f32 v[100:101], v[100:101], v[228:229]
	v_pk_mul_f32 v[102:103], v[102:103], v[230:231]
	s_nop 1
	v_mfma_f32_16x16x32_bf16 v[100:103], v[220:223], v[216:219], v[100:103]
	ds_read_b128 v[220:223], v9 offset:22528
	ds_read_b128 v[228:231], v10 offset:38144
	s_waitcnt lgkmcnt(2)
	v_pk_mul_f32 v[104:105], v[104:105], v[232:233]
	v_pk_mul_f32 v[106:107], v[106:107], v[234:235]
	s_nop 1
	v_mfma_f32_16x16x32_bf16 v[104:107], v[224:227], v[216:219], v[104:107]
	ds_read_b128 v[224:227], v9 offset:23808
	ds_read_b128 v[232:235], v10 offset:38208
	s_waitcnt lgkmcnt(2)
	v_pk_mul_f32 v[108:109], v[108:109], v[228:229]
	v_pk_mul_f32 v[110:111], v[110:111], v[230:231]
	s_nop 1
	v_mfma_f32_16x16x32_bf16 v[108:111], v[220:223], v[216:219], v[108:111]
	ds_read_b128 v[220:223], v9 offset:25088
	ds_read_b128 v[228:231], v10 offset:38272
	s_waitcnt lgkmcnt(2)
	v_pk_mul_f32 v[112:113], v[112:113], v[232:233]
	v_pk_mul_f32 v[114:115], v[114:115], v[234:235]
	s_nop 1
	v_mfma_f32_16x16x32_bf16 v[112:115], v[224:227], v[216:219], v[112:115]
	ds_read_b128 v[224:227], v9 offset:26368
	ds_read_b128 v[232:235], v10 offset:38336
	s_waitcnt lgkmcnt(2)
	v_pk_mul_f32 v[116:117], v[116:117], v[228:229]
	v_pk_mul_f32 v[118:119], v[118:119], v[230:231]
	s_nop 1
	v_mfma_f32_16x16x32_bf16 v[116:119], v[220:223], v[216:219], v[116:119]
	s_waitcnt lgkmcnt(0)
	v_pk_mul_f32 v[120:121], v[120:121], v[232:233]
	v_pk_mul_f32 v[122:123], v[122:123], v[234:235]
	s_nop 1
	v_mfma_f32_16x16x32_bf16 v[120:123], v[224:227], v[216:219], v[120:123]
	ds_write_b32 v11, v136
	ds_write_b32 v11, v140 offset:8448
	ds_write_b32 v11, v137 offset:528
	ds_write_b32 v11, v141 offset:8976
	ds_write_b32 v11, v138 offset:1056
	ds_write_b32 v11, v142 offset:9504
	ds_write_b32 v11, v139 offset:1584
	ds_write_b32 v11, v143 offset:10032
	ds_read_b32 v200, v0 offset:55296
	ds_read_b32 v201, v0 offset:55808
	ds_read_b32 v202, v0 offset:56320
	ds_read_b32 v203, v0 offset:56832
	v_lshl_or_b32 v220, v85, 16, v84
	v_lshl_or_b32 v221, v87, 16, v86
	v_lshl_or_b32 v222, v89, 16, v88
	v_lshl_or_b32 v223, v91, 16, v90
	ds_write_b128 v4, v[220:223] offset:27648
	s_waitcnt lgkmcnt(1)
	v_mul_f32_e32 v204, v21, v200
	v_fmac_f32_e32 v204, v22, v201
	v_fmac_f32_e32 v204, v23, v202
	v_add_f32_e32 v205, v200, v201
	v_add_f32_e32 v205, v205, v202
	v_add_f32_e32 v205, v205, v203
	v_add_f32_e32 v218, v204, v68
	v_mul_f32_e32 v207, 0x3fb8aa3b, v60
	v_exp_f32_e32 v207, v207
	v_lshlrev_b32_e32 v209, 16, v76
	v_sub_f32_e32 v208, 1.0, v207
	v_mul_f32_e32 v207, 0x3fb8aa3b, v218
	v_exp_f32_e32 v207, v207
	v_add_f32_e32 v206, v218, v24
	v_mul_f32_e32 v224, v209, v207
	v_mul_f32_e32 v206, 0x3fb8aa3b, v206
	v_exp_f32_e32 v206, v206
	v_sub_f32_e32 v207, v205, v218
	v_mul_f32_e32 v60, v209, v206
	v_mul_f32_e32 v207, 0x3fb8aa3b, v207
	v_exp_f32_e32 v207, v207
	v_min_f32_e64 v206, -v218, s29
	v_mul_f32_e32 v210, v208, v207
	v_mul_f32_e32 v206, 0x3fb8aa3b, v206
	v_exp_f32_e32 v206, v206
	s_nop 0
	v_mul_f32_e32 v232, v208, v206
	v_add_f32_e32 v218, v204, v69
	v_mul_f32_e32 v207, 0x3fb8aa3b, v61
	v_exp_f32_e32 v207, v207
	v_lshlrev_b32_e32 v209, 16, v77
	v_sub_f32_e32 v208, 1.0, v207
	v_mul_f32_e32 v207, 0x3fb8aa3b, v218
	v_exp_f32_e32 v207, v207
	v_add_f32_e32 v206, v218, v24
	v_mul_f32_e32 v225, v209, v207
	v_mul_f32_e32 v206, 0x3fb8aa3b, v206
	v_exp_f32_e32 v206, v206
	v_sub_f32_e32 v207, v205, v218
	v_mul_f32_e32 v61, v209, v206
	v_mul_f32_e32 v207, 0x3fb8aa3b, v207
	v_exp_f32_e32 v207, v207
	v_min_f32_e64 v206, -v218, s29
	v_mul_f32_e32 v211, v208, v207
	v_mul_f32_e32 v206, 0x3fb8aa3b, v206
	v_exp_f32_e32 v206, v206
	s_nop 0
	v_mul_f32_e32 v233, v208, v206
	v_add_f32_e32 v218, v204, v70
	v_mul_f32_e32 v207, 0x3fb8aa3b, v62
	v_exp_f32_e32 v207, v207
	v_lshlrev_b32_e32 v209, 16, v78
	v_sub_f32_e32 v208, 1.0, v207
	v_mul_f32_e32 v207, 0x3fb8aa3b, v218
	v_exp_f32_e32 v207, v207
	v_add_f32_e32 v206, v218, v24
	v_mul_f32_e32 v226, v209, v207
	v_mul_f32_e32 v206, 0x3fb8aa3b, v206
	v_exp_f32_e32 v206, v206
	v_sub_f32_e32 v207, v205, v218
	v_mul_f32_e32 v62, v209, v206
	v_mul_f32_e32 v207, 0x3fb8aa3b, v207
	v_exp_f32_e32 v207, v207
	v_min_f32_e64 v206, -v218, s29
	v_mul_f32_e32 v212, v208, v207
	v_mul_f32_e32 v206, 0x3fb8aa3b, v206
	v_exp_f32_e32 v206, v206
	s_nop 0
	v_mul_f32_e32 v234, v208, v206
	v_add_f32_e32 v218, v204, v71
	v_mul_f32_e32 v207, 0x3fb8aa3b, v63
	v_exp_f32_e32 v207, v207
	v_lshlrev_b32_e32 v209, 16, v79
	v_sub_f32_e32 v208, 1.0, v207
	v_mul_f32_e32 v207, 0x3fb8aa3b, v218
	v_exp_f32_e32 v207, v207
	v_add_f32_e32 v206, v218, v24
	v_mul_f32_e32 v227, v209, v207
	v_mul_f32_e32 v206, 0x3fb8aa3b, v206
	v_exp_f32_e32 v206, v206
	v_sub_f32_e32 v207, v205, v218
	v_mul_f32_e32 v63, v209, v206
	v_mul_f32_e32 v207, 0x3fb8aa3b, v207
	v_exp_f32_e32 v207, v207
	v_min_f32_e64 v206, -v218, s29
	v_mul_f32_e32 v213, v208, v207
	v_mul_f32_e32 v206, 0x3fb8aa3b, v206
	v_exp_f32_e32 v206, v206
	s_nop 0
	v_mul_f32_e32 v235, v208, v206
	v_add_f32_e32 v218, v204, v72
	v_mul_f32_e32 v207, 0x3fb8aa3b, v64
	v_exp_f32_e32 v207, v207
	v_lshlrev_b32_e32 v209, 16, v80
	v_sub_f32_e32 v208, 1.0, v207
	v_mul_f32_e32 v207, 0x3fb8aa3b, v218
	v_exp_f32_e32 v207, v207
	v_add_f32_e32 v206, v218, v24
	v_mul_f32_e32 v228, v209, v207
	v_mul_f32_e32 v206, 0x3fb8aa3b, v206
	v_exp_f32_e32 v206, v206
	v_sub_f32_e32 v207, v205, v218
	v_mul_f32_e32 v64, v209, v206
	v_mul_f32_e32 v207, 0x3fb8aa3b, v207
	v_exp_f32_e32 v207, v207
	v_min_f32_e64 v206, -v218, s29
	v_mul_f32_e32 v214, v208, v207
	v_mul_f32_e32 v206, 0x3fb8aa3b, v206
	v_exp_f32_e32 v206, v206
	s_nop 0
	v_mul_f32_e32 v236, v208, v206
	v_add_f32_e32 v218, v204, v73
	v_mul_f32_e32 v207, 0x3fb8aa3b, v65
	v_exp_f32_e32 v207, v207
	v_lshlrev_b32_e32 v209, 16, v81
	v_sub_f32_e32 v208, 1.0, v207
	v_mul_f32_e32 v207, 0x3fb8aa3b, v218
	v_exp_f32_e32 v207, v207
	v_add_f32_e32 v206, v218, v24
	v_mul_f32_e32 v229, v209, v207
	v_mul_f32_e32 v206, 0x3fb8aa3b, v206
	v_exp_f32_e32 v206, v206
	v_sub_f32_e32 v207, v205, v218
	v_mul_f32_e32 v65, v209, v206
	v_mul_f32_e32 v207, 0x3fb8aa3b, v207
	v_exp_f32_e32 v207, v207
	v_min_f32_e64 v206, -v218, s29
	v_mul_f32_e32 v215, v208, v207
	v_mul_f32_e32 v206, 0x3fb8aa3b, v206
	v_exp_f32_e32 v206, v206
	s_nop 0
	v_mul_f32_e32 v237, v208, v206
	v_add_f32_e32 v218, v204, v74
	v_mul_f32_e32 v207, 0x3fb8aa3b, v66
	v_exp_f32_e32 v207, v207
	v_lshlrev_b32_e32 v209, 16, v82
	v_sub_f32_e32 v208, 1.0, v207
	v_mul_f32_e32 v207, 0x3fb8aa3b, v218
	v_exp_f32_e32 v207, v207
	v_add_f32_e32 v206, v218, v24
	v_mul_f32_e32 v230, v209, v207
	v_mul_f32_e32 v206, 0x3fb8aa3b, v206
	v_exp_f32_e32 v206, v206
	v_sub_f32_e32 v207, v205, v218
	v_mul_f32_e32 v66, v209, v206
	v_mul_f32_e32 v207, 0x3fb8aa3b, v207
	v_exp_f32_e32 v207, v207
	v_min_f32_e64 v206, -v218, s29
	v_mul_f32_e32 v216, v208, v207
	v_mul_f32_e32 v206, 0x3fb8aa3b, v206
	v_exp_f32_e32 v206, v206
	s_nop 0
	v_mul_f32_e32 v238, v208, v206
	v_add_f32_e32 v218, v204, v75
	v_mul_f32_e32 v207, 0x3fb8aa3b, v67
	v_exp_f32_e32 v207, v207
	v_lshlrev_b32_e32 v209, 16, v83
	v_sub_f32_e32 v208, 1.0, v207
	v_mul_f32_e32 v207, 0x3fb8aa3b, v218
	v_exp_f32_e32 v207, v207
	v_add_f32_e32 v206, v218, v24
	v_mul_f32_e32 v231, v209, v207
	v_mul_f32_e32 v206, 0x3fb8aa3b, v206
	v_exp_f32_e32 v206, v206
	v_sub_f32_e32 v207, v205, v218
	v_mul_f32_e32 v67, v209, v206
	v_mul_f32_e32 v207, 0x3fb8aa3b, v207
	v_exp_f32_e32 v207, v207
	v_min_f32_e64 v206, -v218, s29
	v_mul_f32_e32 v217, v208, v207
	v_mul_f32_e32 v206, 0x3fb8aa3b, v206
	v_exp_f32_e32 v206, v206
	s_nop 0
	v_mul_f32_e32 v239, v208, v206
	v_cvt_pk_bf16_f32 v224, v224, v225
	ds_write_b16 v2, v224
	ds_write_b16_d16_hi v2, v224 offset:272
	v_cvt_pk_bf16_f32 v232, v232, v233
	ds_write_b16 v2, v232 offset:8704
	ds_write_b16_d16_hi v2, v232 offset:8976
	v_cvt_pk_bf16_f32 v226, v226, v227
	ds_write_b16 v2, v226 offset:544
	ds_write_b16_d16_hi v2, v226 offset:816
	v_cvt_pk_bf16_f32 v234, v234, v235
	ds_write_b16 v2, v234 offset:9248
	ds_write_b16_d16_hi v2, v234 offset:9520
	v_cvt_pk_bf16_f32 v228, v228, v229
	ds_write_b16 v2, v228 offset:1088
	ds_write_b16_d16_hi v2, v228 offset:1360
	v_cvt_pk_bf16_f32 v236, v236, v237
	ds_write_b16 v2, v236 offset:9792
	ds_write_b16_d16_hi v2, v236 offset:10064
	v_cvt_pk_bf16_f32 v230, v230, v231
	ds_write_b16 v2, v230 offset:1632
	ds_write_b16_d16_hi v2, v230 offset:1904
	v_cvt_pk_bf16_f32 v238, v238, v239
	ds_write_b16 v2, v238 offset:10336
	ds_write_b16_d16_hi v2, v238 offset:10608
	v_cvt_pk_bf16_f32 v210, v210, v211
	v_cvt_pk_bf16_f32 v211, v212, v213
	v_cvt_pk_bf16_f32 v212, v214, v215
	v_cvt_pk_bf16_f32 v213, v216, v217
	ds_write_b128 v4, v[210:213] offset:17408
	v_cvt_pk_bf16_f32 v60, v60, v61
	v_cvt_pk_bf16_f32 v62, v62, v63
	v_cvt_pk_bf16_f32 v64, v64, v65
	v_cvt_pk_bf16_f32 v66, v66, v67
	global_store_short v18, v60, s[12:13]
	global_store_short_d16_hi v18, v60, s[12:13] offset:1536
	global_store_short v18, v62, s[12:13] offset:3072
	global_store_short_d16_hi v19, v62, s[12:13]
	global_store_short v19, v64, s[12:13] offset:1536
	global_store_short_d16_hi v19, v64, s[12:13] offset:3072
	global_store_short v20, v66, s[12:13]
	global_store_short_d16_hi v20, v66, s[12:13] offset:1536
	s_add_u32 s12, s12, 0xc000
	s_addc_u32 s13, s13, 0
	s_cmp_gt_u32 s18, 1
	s_cbranch_scc1 .Lhg_w01_5
	v_mul_f32_e32 v207, 0x3fb8aa3b, v205
	v_exp_f32_e32 v207, v207
	s_nop 0
	ds_write_b32 v26, v207 offset:37888
.Lhg_w01_5:
	v_add_f32_e32 v24, v24, v205
	s_branch .Lhg_joined_4
.Lhg_bfirst_3:
	ds_read_b32 v200, v0 offset:55296
	ds_read_b32 v201, v0 offset:55808
	ds_read_b32 v202, v0 offset:56320
	ds_read_b32 v203, v0 offset:56832
	v_lshl_or_b32 v220, v85, 16, v84
	v_lshl_or_b32 v221, v87, 16, v86
	v_lshl_or_b32 v222, v89, 16, v88
	v_lshl_or_b32 v223, v91, 16, v90
	ds_write_b128 v4, v[220:223] offset:27648
	s_waitcnt lgkmcnt(1)
	v_mul_f32_e32 v204, v21, v200
	v_fmac_f32_e32 v204, v22, v201
	v_fmac_f32_e32 v204, v23, v202
	v_add_f32_e32 v205, v200, v201
	v_add_f32_e32 v205, v205, v202
	v_add_f32_e32 v205, v205, v203
	v_add_f32_e32 v218, v204, v68
	v_mul_f32_e32 v207, 0x3fb8aa3b, v60
	v_exp_f32_e32 v207, v207
	v_lshlrev_b32_e32 v209, 16, v76
	v_sub_f32_e32 v208, 1.0, v207
	v_mul_f32_e32 v207, 0x3fb8aa3b, v218
	v_exp_f32_e32 v207, v207
	v_add_f32_e32 v206, v218, v24
	v_mul_f32_e32 v224, v209, v207
	v_mul_f32_e32 v206, 0x3fb8aa3b, v206
	v_exp_f32_e32 v206, v206
	v_sub_f32_e32 v207, v205, v218
	v_mul_f32_e32 v60, v209, v206
	v_mul_f32_e32 v207, 0x3fb8aa3b, v207
	v_exp_f32_e32 v207, v207
	v_min_f32_e64 v206, -v218, s29
	v_mul_f32_e32 v210, v208, v207
	v_mul_f32_e32 v206, 0x3fb8aa3b, v206
	v_exp_f32_e32 v206, v206
	s_nop 0
	v_mul_f32_e32 v232, v208, v206
	v_add_f32_e32 v218, v204, v69
	v_mul_f32_e32 v207, 0x3fb8aa3b, v61
	v_exp_f32_e32 v207, v207
	v_lshlrev_b32_e32 v209, 16, v77
	v_sub_f32_e32 v208, 1.0, v207
	v_mul_f32_e32 v207, 0x3fb8aa3b, v218
	v_exp_f32_e32 v207, v207
	v_add_f32_e32 v206, v218, v24
	v_mul_f32_e32 v225, v209, v207
	v_mul_f32_e32 v206, 0x3fb8aa3b, v206
	v_exp_f32_e32 v206, v206
	v_sub_f32_e32 v207, v205, v218
	v_mul_f32_e32 v61, v209, v206
	v_mul_f32_e32 v207, 0x3fb8aa3b, v207
	v_exp_f32_e32 v207, v207
	v_min_f32_e64 v206, -v218, s29
	v_mul_f32_e32 v211, v208, v207
	v_mul_f32_e32 v206, 0x3fb8aa3b, v206
	v_exp_f32_e32 v206, v206
	s_nop 0
	v_mul_f32_e32 v233, v208, v206
	v_add_f32_e32 v218, v204, v70
	v_mul_f32_e32 v207, 0x3fb8aa3b, v62
	v_exp_f32_e32 v207, v207
	v_lshlrev_b32_e32 v209, 16, v78
	v_sub_f32_e32 v208, 1.0, v207
	v_mul_f32_e32 v207, 0x3fb8aa3b, v218
	v_exp_f32_e32 v207, v207
	v_add_f32_e32 v206, v218, v24
	v_mul_f32_e32 v226, v209, v207
	v_mul_f32_e32 v206, 0x3fb8aa3b, v206
	v_exp_f32_e32 v206, v206
	v_sub_f32_e32 v207, v205, v218
	v_mul_f32_e32 v62, v209, v206
	v_mul_f32_e32 v207, 0x3fb8aa3b, v207
	v_exp_f32_e32 v207, v207
	v_min_f32_e64 v206, -v218, s29
	v_mul_f32_e32 v212, v208, v207
	v_mul_f32_e32 v206, 0x3fb8aa3b, v206
	v_exp_f32_e32 v206, v206
	s_nop 0
	v_mul_f32_e32 v234, v208, v206
	v_add_f32_e32 v218, v204, v71
	v_mul_f32_e32 v207, 0x3fb8aa3b, v63
	v_exp_f32_e32 v207, v207
	v_lshlrev_b32_e32 v209, 16, v79
	v_sub_f32_e32 v208, 1.0, v207
	v_mul_f32_e32 v207, 0x3fb8aa3b, v218
	v_exp_f32_e32 v207, v207
	v_add_f32_e32 v206, v218, v24
	v_mul_f32_e32 v227, v209, v207
	v_mul_f32_e32 v206, 0x3fb8aa3b, v206
	v_exp_f32_e32 v206, v206
	v_sub_f32_e32 v207, v205, v218
	v_mul_f32_e32 v63, v209, v206
	v_mul_f32_e32 v207, 0x3fb8aa3b, v207
	v_exp_f32_e32 v207, v207
	v_min_f32_e64 v206, -v218, s29
	v_mul_f32_e32 v213, v208, v207
	v_mul_f32_e32 v206, 0x3fb8aa3b, v206
	v_exp_f32_e32 v206, v206
	s_nop 0
	v_mul_f32_e32 v235, v208, v206
	v_add_f32_e32 v218, v204, v72
	v_mul_f32_e32 v207, 0x3fb8aa3b, v64
	v_exp_f32_e32 v207, v207
	v_lshlrev_b32_e32 v209, 16, v80
	v_sub_f32_e32 v208, 1.0, v207
	v_mul_f32_e32 v207, 0x3fb8aa3b, v218
	v_exp_f32_e32 v207, v207
	v_add_f32_e32 v206, v218, v24
	v_mul_f32_e32 v228, v209, v207
	v_mul_f32_e32 v206, 0x3fb8aa3b, v206
	v_exp_f32_e32 v206, v206
	v_sub_f32_e32 v207, v205, v218
	v_mul_f32_e32 v64, v209, v206
	v_mul_f32_e32 v207, 0x3fb8aa3b, v207
	v_exp_f32_e32 v207, v207
	v_min_f32_e64 v206, -v218, s29
	v_mul_f32_e32 v214, v208, v207
	v_mul_f32_e32 v206, 0x3fb8aa3b, v206
	v_exp_f32_e32 v206, v206
	s_nop 0
	v_mul_f32_e32 v236, v208, v206
	v_add_f32_e32 v218, v204, v73
	v_mul_f32_e32 v207, 0x3fb8aa3b, v65
	v_exp_f32_e32 v207, v207
	v_lshlrev_b32_e32 v209, 16, v81
	v_sub_f32_e32 v208, 1.0, v207
	v_mul_f32_e32 v207, 0x3fb8aa3b, v218
	v_exp_f32_e32 v207, v207
	v_add_f32_e32 v206, v218, v24
	v_mul_f32_e32 v229, v209, v207
	v_mul_f32_e32 v206, 0x3fb8aa3b, v206
	v_exp_f32_e32 v206, v206
	v_sub_f32_e32 v207, v205, v218
	v_mul_f32_e32 v65, v209, v206
	v_mul_f32_e32 v207, 0x3fb8aa3b, v207
	v_exp_f32_e32 v207, v207
	v_min_f32_e64 v206, -v218, s29
	v_mul_f32_e32 v215, v208, v207
	v_mul_f32_e32 v206, 0x3fb8aa3b, v206
	v_exp_f32_e32 v206, v206
	s_nop 0
	v_mul_f32_e32 v237, v208, v206
	v_add_f32_e32 v218, v204, v74
	v_mul_f32_e32 v207, 0x3fb8aa3b, v66
	v_exp_f32_e32 v207, v207
	v_lshlrev_b32_e32 v209, 16, v82
	v_sub_f32_e32 v208, 1.0, v207
	v_mul_f32_e32 v207, 0x3fb8aa3b, v218
	v_exp_f32_e32 v207, v207
	v_add_f32_e32 v206, v218, v24
	v_mul_f32_e32 v230, v209, v207
	v_mul_f32_e32 v206, 0x3fb8aa3b, v206
	v_exp_f32_e32 v206, v206
	v_sub_f32_e32 v207, v205, v218
	v_mul_f32_e32 v66, v209, v206
	v_mul_f32_e32 v207, 0x3fb8aa3b, v207
	v_exp_f32_e32 v207, v207
	v_min_f32_e64 v206, -v218, s29
	v_mul_f32_e32 v216, v208, v207
	v_mul_f32_e32 v206, 0x3fb8aa3b, v206
	v_exp_f32_e32 v206, v206
	s_nop 0
	v_mul_f32_e32 v238, v208, v206
	v_add_f32_e32 v218, v204, v75
	v_mul_f32_e32 v207, 0x3fb8aa3b, v67
	v_exp_f32_e32 v207, v207
	v_lshlrev_b32_e32 v209, 16, v83
	v_sub_f32_e32 v208, 1.0, v207
	v_mul_f32_e32 v207, 0x3fb8aa3b, v218
	v_exp_f32_e32 v207, v207
	v_add_f32_e32 v206, v218, v24
	v_mul_f32_e32 v231, v209, v207
	v_mul_f32_e32 v206, 0x3fb8aa3b, v206
	v_exp_f32_e32 v206, v206
	v_sub_f32_e32 v207, v205, v218
	v_mul_f32_e32 v67, v209, v206
	v_mul_f32_e32 v207, 0x3fb8aa3b, v207
	v_exp_f32_e32 v207, v207
	v_min_f32_e64 v206, -v218, s29
	v_mul_f32_e32 v217, v208, v207
	v_mul_f32_e32 v206, 0x3fb8aa3b, v206
	v_exp_f32_e32 v206, v206
	s_nop 0
	v_mul_f32_e32 v239, v208, v206
	v_cvt_pk_bf16_f32 v224, v224, v225
	ds_write_b16 v2, v224
	ds_write_b16_d16_hi v2, v224 offset:272
	v_cvt_pk_bf16_f32 v232, v232, v233
	ds_write_b16 v2, v232 offset:8704
	ds_write_b16_d16_hi v2, v232 offset:8976
	v_cvt_pk_bf16_f32 v226, v226, v227
	ds_write_b16 v2, v226 offset:544
	ds_write_b16_d16_hi v2, v226 offset:816
	v_cvt_pk_bf16_f32 v234, v234, v235
	ds_write_b16 v2, v234 offset:9248
	ds_write_b16_d16_hi v2, v234 offset:9520
	v_cvt_pk_bf16_f32 v228, v228, v229
	ds_write_b16 v2, v228 offset:1088
	ds_write_b16_d16_hi v2, v228 offset:1360
	v_cvt_pk_bf16_f32 v236, v236, v237
	ds_write_b16 v2, v236 offset:9792
	ds_write_b16_d16_hi v2, v236 offset:10064
	v_cvt_pk_bf16_f32 v230, v230, v231
	ds_write_b16 v2, v230 offset:1632
	ds_write_b16_d16_hi v2, v230 offset:1904
	v_cvt_pk_bf16_f32 v238, v238, v239
	ds_write_b16 v2, v238 offset:10336
	ds_write_b16_d16_hi v2, v238 offset:10608
	v_cvt_pk_bf16_f32 v210, v210, v211
	v_cvt_pk_bf16_f32 v211, v212, v213
	v_cvt_pk_bf16_f32 v212, v214, v215
	v_cvt_pk_bf16_f32 v213, v216, v217
	ds_write_b128 v4, v[210:213] offset:17408
	v_cvt_pk_bf16_f32 v60, v60, v61
	v_cvt_pk_bf16_f32 v62, v62, v63
	v_cvt_pk_bf16_f32 v64, v64, v65
	v_cvt_pk_bf16_f32 v66, v66, v67
	global_store_short v18, v60, s[12:13]
	global_store_short_d16_hi v18, v60, s[12:13] offset:1536
	global_store_short v18, v62, s[12:13] offset:3072
	global_store_short_d16_hi v19, v62, s[12:13]
	global_store_short v19, v64, s[12:13] offset:1536
	global_store_short_d16_hi v19, v64, s[12:13] offset:3072
	global_store_short v20, v66, s[12:13]
	global_store_short_d16_hi v20, v66, s[12:13] offset:1536
	s_add_u32 s12, s12, 0xc000
	s_addc_u32 s13, s13, 0
	s_cmp_gt_u32 s18, 1
	s_cbranch_scc1 .Lhg_w01_6
	v_mul_f32_e32 v207, 0x3fb8aa3b, v205
	v_exp_f32_e32 v207, v207
	s_nop 0
	ds_write_b32 v26, v207 offset:37888
.Lhg_w01_6:
	v_add_f32_e32 v24, v24, v205
	ds_read_b128 v[144:147], v5 offset:8704
	ds_read_b128 v[148:151], v5 offset:13056
	ds_read_b128 v[152:155], v5 offset:0
	ds_read_b128 v[172:175], v5 offset:4352
	ds_read_b128 v[176:179], v5 offset:8768
	ds_read_b128 v[180:183], v5 offset:13120
	ds_read_b128 v[184:187], v5 offset:64
	ds_read_b128 v[188:191], v5 offset:4416
	s_waitcnt lgkmcnt(4)
	v_mfma_f32_16x16x32_bf16 v[124:127], v[144:147], v[152:155], 0
	v_mfma_f32_16x16x32_bf16 v[128:131], v[144:147], v[172:175], 0
	v_mfma_f32_16x16x32_bf16 v[132:135], v[148:151], v[172:175], 0
	ds_read_b128 v[144:147], v5 offset:8832
	ds_read_b128 v[148:151], v5 offset:13184
	ds_read_b128 v[152:155], v5 offset:128
	ds_read_b128 v[172:175], v5 offset:4480
	s_waitcnt lgkmcnt(4)
	v_mfma_f32_16x16x32_bf16 v[124:127], v[176:179], v[184:187], v[124:127]
	v_mfma_f32_16x16x32_bf16 v[128:131], v[176:179], v[188:191], v[128:131]
	v_mfma_f32_16x16x32_bf16 v[132:135], v[180:183], v[188:191], v[132:135]
	ds_read_b128 v[176:179], v5 offset:8896
	ds_read_b128 v[180:183], v5 offset:13248
	ds_read_b128 v[184:187], v5 offset:192
	ds_read_b128 v[188:191], v5 offset:4544
	s_waitcnt lgkmcnt(4)
	v_mfma_f32_16x16x32_bf16 v[124:127], v[144:147], v[152:155], v[124:127]
	v_mfma_f32_16x16x32_bf16 v[128:131], v[144:147], v[172:175], v[128:131]
	v_mfma_f32_16x16x32_bf16 v[132:135], v[148:151], v[172:175], v[132:135]
	s_waitcnt lgkmcnt(0)
	v_mfma_f32_16x16x32_bf16 v[124:127], v[176:179], v[184:187], v[124:127]
	v_mfma_f32_16x16x32_bf16 v[128:131], v[176:179], v[188:191], v[128:131]
	v_mfma_f32_16x16x32_bf16 v[132:135], v[180:183], v[188:191], v[132:135]
	ds_read_b64 v[204:205], v6
	ds_read_b64 v[206:207], v6 offset:32
	ds_read_b64 v[208:209], v6 offset:4352
	ds_read_b64 v[210:211], v6 offset:4384
	v_cvt_pk_bf16_f32 v200, v92, v93
	v_cvt_pk_bf16_f32 v201, v94, v95
	v_cvt_pk_bf16_f32 v202, v96, v97
	v_cvt_pk_bf16_f32 v203, v98, v99
	s_waitcnt lgkmcnt(0)
	s_nop 1
	v_mfma_f32_16x16x32_bf16 v[136:139], v[204:207], v[200:203], 0
	v_mfma_f32_16x16x32_bf16 v[140:143], v[208:211], v[200:203], 0
	ds_read_b64 v[204:205], v6 offset:64
	ds_read_b64 v[206:207], v6 offset:96
	ds_read_b64 v[208:209], v6 offset:4416
	ds_read_b64 v[210:211], v6 offset:4448
	v_cvt_pk_bf16_f32 v200, v100, v101
	v_cvt_pk_bf16_f32 v201, v102, v103
	v_cvt_pk_bf16_f32 v202, v104, v105
	v_cvt_pk_bf16_f32 v203, v106, v107
	s_waitcnt lgkmcnt(0)
	s_nop 1
	v_mfma_f32_16x16x32_bf16 v[136:139], v[204:207], v[200:203], v[136:139]
	v_mfma_f32_16x16x32_bf16 v[140:143], v[208:211], v[200:203], v[140:143]
	ds_read_b64 v[204:205], v6 offset:128
	ds_read_b64 v[206:207], v6 offset:160
	ds_read_b64 v[208:209], v6 offset:4480
	ds_read_b64 v[210:211], v6 offset:4512
	v_cvt_pk_bf16_f32 v200, v108, v109
	v_cvt_pk_bf16_f32 v201, v110, v111
	v_cvt_pk_bf16_f32 v202, v112, v113
	v_cvt_pk_bf16_f32 v203, v114, v115
	s_waitcnt lgkmcnt(0)
	s_nop 1
	v_mfma_f32_16x16x32_bf16 v[136:139], v[204:207], v[200:203], v[136:139]
	v_mfma_f32_16x16x32_bf16 v[140:143], v[208:211], v[200:203], v[140:143]
	ds_read_b64 v[204:205], v6 offset:192
	ds_read_b64 v[206:207], v6 offset:224
	ds_read_b64 v[208:209], v6 offset:4544
	ds_read_b64 v[210:211], v6 offset:4576
	v_cvt_pk_bf16_f32 v200, v116, v117
	v_cvt_pk_bf16_f32 v201, v118, v119
	v_cvt_pk_bf16_f32 v202, v120, v121
	v_cvt_pk_bf16_f32 v203, v122, v123
	s_waitcnt lgkmcnt(0)
	s_nop 1
	v_mfma_f32_16x16x32_bf16 v[136:139], v[204:207], v[200:203], v[136:139]
	v_mfma_f32_16x16x32_bf16 v[140:143], v[208:211], v[200:203], v[140:143]
	ds_read_b64 v[212:213], v7 offset:27648
	ds_read_b64 v[214:215], v7 offset:27680
	ds_read_b128 v[216:219], v8 offset:27648
	v_cndmask_b32_e64 v124, 0, v124, s[40:41]
	v_cndmask_b32_e64 v132, 0, v132, s[40:41]
	v_cndmask_b32_e64 v125, 0, v125, s[42:43]
	v_cndmask_b32_e64 v133, 0, v133, s[42:43]
	v_cndmask_b32_e64 v126, 0, v126, s[44:45]
	v_cndmask_b32_e64 v134, 0, v134, s[44:45]
	v_cndmask_b32_e64 v127, 0, v127, s[46:47]
	v_cndmask_b32_e64 v135, 0, v135, s[46:47]
	v_cvt_pk_bf16_f32 v124, v124, v125
	v_cvt_pk_bf16_f32 v125, v126, v127
	v_mov_b32_e32 v126, 0
	v_mov_b32_e32 v127, 0
	v_cvt_pk_bf16_f32 v128, v128, v129
	v_cvt_pk_bf16_f32 v129, v130, v131
	v_cvt_pk_bf16_f32 v130, v132, v133
	v_cvt_pk_bf16_f32 v131, v134, v135
	s_waitcnt lgkmcnt(0)
	s_nop 1
	v_mfma_f32_16x16x32_bf16 v[136:139], v[124:127], v[212:215], v[136:139]
	v_mfma_f32_16x16x32_bf16 v[140:143], v[128:131], v[212:215], v[140:143]
	ds_read_b128 v[220:223], v9 offset:17408
	ds_read_b128 v[228:231], v10 offset:37888
	ds_read_b128 v[224:227], v9 offset:18688
	ds_read_b128 v[232:235], v10 offset:37952
	s_waitcnt lgkmcnt(2)
	v_pk_mul_f32 v[92:93], v[92:93], v[228:229]
	v_pk_mul_f32 v[94:95], v[94:95], v[230:231]
	s_nop 1
	v_mfma_f32_16x16x32_bf16 v[92:95], v[220:223], v[216:219], v[92:95]
	ds_read_b128 v[220:223], v9 offset:19968
	ds_read_b128 v[228:231], v10 offset:38016
	s_waitcnt lgkmcnt(2)
	v_pk_mul_f32 v[96:97], v[96:97], v[232:233]
	v_pk_mul_f32 v[98:99], v[98:99], v[234:235]
	s_nop 1
	v_mfma_f32_16x16x32_bf16 v[96:99], v[224:227], v[216:219], v[96:99]
	ds_read_b128 v[224:227], v9 offset:21248
	ds_read_b128 v[232:235], v10 offset:38080
	s_waitcnt lgkmcnt(2)
	v_pk_mul_f32 v[100:101], v[100:101], v[228:229]
	v_pk_mul_f32 v[102:103], v[102:103], v[230:231]
	s_nop 1
	v_mfma_f32_16x16x32_bf16 v[100:103], v[220:223], v[216:219], v[100:103]
	ds_read_b128 v[220:223], v9 offset:22528
	ds_read_b128 v[228:231], v10 offset:38144
	s_waitcnt lgkmcnt(2)
	v_pk_mul_f32 v[104:105], v[104:105], v[232:233]
	v_pk_mul_f32 v[106:107], v[106:107], v[234:235]
	s_nop 1
	v_mfma_f32_16x16x32_bf16 v[104:107], v[224:227], v[216:219], v[104:107]
	ds_read_b128 v[224:227], v9 offset:23808
	ds_read_b128 v[232:235], v10 offset:38208
	s_waitcnt lgkmcnt(2)
	v_pk_mul_f32 v[108:109], v[108:109], v[228:229]
	v_pk_mul_f32 v[110:111], v[110:111], v[230:231]
	s_nop 1
	v_mfma_f32_16x16x32_bf16 v[108:111], v[220:223], v[216:219], v[108:111]
	ds_read_b128 v[220:223], v9 offset:25088
	ds_read_b128 v[228:231], v10 offset:38272
	s_waitcnt lgkmcnt(2)
	v_pk_mul_f32 v[112:113], v[112:113], v[232:233]
	v_pk_mul_f32 v[114:115], v[114:115], v[234:235]
	s_nop 1
	v_mfma_f32_16x16x32_bf16 v[112:115], v[224:227], v[216:219], v[112:115]
	ds_read_b128 v[224:227], v9 offset:26368
	ds_read_b128 v[232:235], v10 offset:38336
	s_waitcnt lgkmcnt(2)
	v_pk_mul_f32 v[116:117], v[116:117], v[228:229]
	v_pk_mul_f32 v[118:119], v[118:119], v[230:231]
	s_nop 1
	v_mfma_f32_16x16x32_bf16 v[116:119], v[220:223], v[216:219], v[116:119]
	s_waitcnt lgkmcnt(0)
	v_pk_mul_f32 v[120:121], v[120:121], v[232:233]
	v_pk_mul_f32 v[122:123], v[122:123], v[234:235]
	s_nop 1
	v_mfma_f32_16x16x32_bf16 v[120:123], v[224:227], v[216:219], v[120:123]
	ds_write_b32 v11, v136
	ds_write_b32 v11, v140 offset:8448
	ds_write_b32 v11, v137 offset:528
	ds_write_b32 v11, v141 offset:8976
	ds_write_b32 v11, v138 offset:1056
	ds_write_b32 v11, v142 offset:9504
	ds_write_b32 v11, v139 offset:1584
	ds_write_b32 v11, v143 offset:10032
.Lhg_joined_4:
	s_waitcnt vmcnt(0) lgkmcnt(0)
	s_barrier
	ds_read_b128 v[200:203], v12
	ds_read_b128 v[204:207], v12 offset:16
	s_waitcnt lgkmcnt(0)
	v_cvt_pk_bf16_f32 v200, v200, v201
	v_cvt_pk_bf16_f32 v201, v202, v203
	v_cvt_pk_bf16_f32 v202, v204, v205
	v_cvt_pk_bf16_f32 v203, v206, v207
	global_store_dwordx4 v13, v[200:203], s[14:15]
	s_add_u32 s14, s14, 0x10000
	s_addc_u32 s15, s15, 0
	v_xor_b32_e32 v2, 0x10000, v2
	v_xor_b32_e32 v4, 0x10000, v4
	v_xor_b32_e32 v26, 0x10000, v26
	v_xor_b32_e32 v5, 0x10000, v5
	v_xor_b32_e32 v6, 0x10000, v6
	v_xor_b32_e32 v7, 0x10000, v7
	v_xor_b32_e32 v8, 0x10000, v8
	v_xor_b32_e32 v9, 0x10000, v9
	v_xor_b32_e32 v10, 0x10000, v10
	s_add_i32 s28, s28, 1
	s_cmp_eq_u32 s28, 31
	s_cbranch_scc1 .Lhg_last
	v_mov_b32_e32 v36, v28
	v_add_f32_e32 v37, v36, v29
	v_add_f32_e32 v38, v37, v30
	v_add_f32_e32 v39, v38, v31
	v_add_f32_e32 v40, v39, v32
	v_add_f32_e32 v41, v40, v33
	v_add_f32_e32 v42, v41, v34
	v_add_f32_e32 v43, v42, v35
	ds_write_b32 v1, v43
	s_waitcnt lgkmcnt(0)
	s_barrier
	s_cmp_gt_u32 s28, 29
	s_cbranch_scc1 .Lhg_noload_7
	global_load_dword v60, v14, s[4:5]
	global_load_dword v61, v14, s[4:5] offset:3072
	global_load_dword v62, v15, s[4:5]
	global_load_dword v63, v15, s[4:5] offset:3072
	global_load_dword v64, v16, s[4:5]
	global_load_dword v65, v16, s[4:5] offset:3072
	global_load_dword v66, v17, s[4:5]
	global_load_dword v67, v17, s[4:5] offset:3072
	global_load_ushort v76, v18, s[8:9]
	global_load_ushort v77, v18, s[8:9] offset:1536
	global_load_ushort v78, v18, s[8:9] offset:3072
	global_load_ushort v79, v19, s[8:9]
	global_load_ushort v80, v19, s[8:9] offset:1536
	global_load_ushort v81, v19, s[8:9] offset:3072
	global_load_ushort v82, v20, s[8:9]
	global_load_ushort v83, v20, s[8:9] offset:1536
	global_load_ushort v84, v18, s[10:11]
	global_load_ushort v85, v18, s[10:11] offset:1536
	global_load_ushort v86, v18, s[10:11] offset:3072
	global_load_ushort v87, v19, s[10:11]
	global_load_ushort v88, v19, s[10:11] offset:1536
	global_load_ushort v89, v19, s[10:11] offset:3072
	global_load_ushort v90, v20, s[10:11]
	global_load_ushort v91, v20, s[10:11] offset:1536
	s_add_u32 s4, s4, 0x18000
	s_addc_u32 s5, s5, 0
	s_add_u32 s8, s8, 0xc000
	s_addc_u32 s9, s9, 0
	s_add_u32 s10, s10, 0xc000
	s_addc_u32 s11, s11, 0
.Lhg_noload_7:
	s_cmp_gt_u32 s18, 3
	s_cbranch_scc1 .Lhg_bfirst_8
	ds_read_b128 v[144:147], v5 offset:8704
	ds_read_b128 v[148:151], v5 offset:13056
	ds_read_b128 v[152:155], v5 offset:0
	ds_read_b128 v[172:175], v5 offset:4352
	ds_read_b128 v[176:179], v5 offset:8768
	ds_read_b128 v[180:183], v5 offset:13120
	ds_read_b128 v[184:187], v5 offset:64
	ds_read_b128 v[188:191], v5 offset:4416
	s_waitcnt lgkmcnt(4)
	v_mfma_f32_16x16x32_bf16 v[124:127], v[144:147], v[152:155], 0
	v_mfma_f32_16x16x32_bf16 v[128:131], v[144:147], v[172:175], 0
	v_mfma_f32_16x16x32_bf16 v[132:135], v[148:151], v[172:175], 0
	ds_read_b128 v[144:147], v5 offset:8832
	ds_read_b128 v[148:151], v5 offset:13184
	ds_read_b128 v[152:155], v5 offset:128
	ds_read_b128 v[172:175], v5 offset:4480
	s_waitcnt lgkmcnt(4)
	v_mfma_f32_16x16x32_bf16 v[124:127], v[176:179], v[184:187], v[124:127]
	v_mfma_f32_16x16x32_bf16 v[128:131], v[176:179], v[188:191], v[128:131]
	v_mfma_f32_16x16x32_bf16 v[132:135], v[180:183], v[188:191], v[132:135]
	ds_read_b128 v[176:179], v5 offset:8896
	ds_read_b128 v[180:183], v5 offset:13248
	ds_read_b128 v[184:187], v5 offset:192
	ds_read_b128 v[188:191], v5 offset:4544
	s_waitcnt lgkmcnt(4)
	v_mfma_f32_16x16x32_bf16 v[124:127], v[144:147], v[152:155], v[124:127]
	v_mfma_f32_16x16x32_bf16 v[128:131], v[144:147], v[172:175], v[128:131]
	v_mfma_f32_16x16x32_bf16 v[132:135], v[148:151], v[172:175], v[132:135]
	s_waitcnt lgkmcnt(0)
	v_mfma_f32_16x16x32_bf16 v[124:127], v[176:179], v[184:187], v[124:127]
	v_mfma_f32_16x16x32_bf16 v[128:131], v[176:179], v[188:191], v[128:131]
	v_mfma_f32_16x16x32_bf16 v[132:135], v[180:183], v[188:191], v[132:135]
	ds_read_b64 v[204:205], v6
	ds_read_b64 v[206:207], v6 offset:32
	ds_read_b64 v[208:209], v6 offset:4352
	ds_read_b64 v[210:211], v6 offset:4384
	v_cvt_pk_bf16_f32 v200, v92, v93
	v_cvt_pk_bf16_f32 v201, v94, v95
	v_cvt_pk_bf16_f32 v202, v96, v97
	v_cvt_pk_bf16_f32 v203, v98, v99
	s_waitcnt lgkmcnt(0)
	s_nop 1
	v_mfma_f32_16x16x32_bf16 v[136:139], v[204:207], v[200:203], 0
	v_mfma_f32_16x16x32_bf16 v[140:143], v[208:211], v[200:203], 0
	ds_read_b64 v[204:205], v6 offset:64
	ds_read_b64 v[206:207], v6 offset:96
	ds_read_b64 v[208:209], v6 offset:4416
	ds_read_b64 v[210:211], v6 offset:4448
	v_cvt_pk_bf16_f32 v200, v100, v101
	v_cvt_pk_bf16_f32 v201, v102, v103
	v_cvt_pk_bf16_f32 v202, v104, v105
	v_cvt_pk_bf16_f32 v203, v106, v107
	s_waitcnt lgkmcnt(0)
	s_nop 1
	v_mfma_f32_16x16x32_bf16 v[136:139], v[204:207], v[200:203], v[136:139]
	v_mfma_f32_16x16x32_bf16 v[140:143], v[208:211], v[200:203], v[140:143]
	ds_read_b64 v[204:205], v6 offset:128
	ds_read_b64 v[206:207], v6 offset:160
	ds_read_b64 v[208:209], v6 offset:4480
	ds_read_b64 v[210:211], v6 offset:4512
	v_cvt_pk_bf16_f32 v200, v108, v109
	v_cvt_pk_bf16_f32 v201, v110, v111
	v_cvt_pk_bf16_f32 v202, v112, v113
	v_cvt_pk_bf16_f32 v203, v114, v115
	s_waitcnt lgkmcnt(0)
	s_nop 1
	v_mfma_f32_16x16x32_bf16 v[136:139], v[204:207], v[200:203], v[136:139]
	v_mfma_f32_16x16x32_bf16 v[140:143], v[208:211], v[200:203], v[140:143]
	ds_read_b64 v[204:205], v6 offset:192
	ds_read_b64 v[206:207], v6 offset:224
	ds_read_b64 v[208:209], v6 offset:4544
	ds_read_b64 v[210:211], v6 offset:4576
	v_cvt_pk_bf16_f32 v200, v116, v117
	v_cvt_pk_bf16_f32 v201, v118, v119
	v_cvt_pk_bf16_f32 v202, v120, v121
	v_cvt_pk_bf16_f32 v203, v122, v123
	s_waitcnt lgkmcnt(0)
	s_nop 1
	v_mfma_f32_16x16x32_bf16 v[136:139], v[204:207], v[200:203], v[136:139]
	v_mfma_f32_16x16x32_bf16 v[140:143], v[208:211], v[200:203], v[140:143]
	ds_read_b64 v[212:213], v7 offset:27648
	ds_read_b64 v[214:215], v7 offset:27680
	ds_read_b128 v[216:219], v8 offset:27648
	v_cndmask_b32_e64 v124, 0, v124, s[40:41]
	v_cndmask_b32_e64 v132, 0, v132, s[40:41]
	v_cndmask_b32_e64 v125, 0, v125, s[42:43]
	v_cndmask_b32_e64 v133, 0, v133, s[42:43]
	v_cndmask_b32_e64 v126, 0, v126, s[44:45]
	v_cndmask_b32_e64 v134, 0, v134, s[44:45]
	v_cndmask_b32_e64 v127, 0, v127, s[46:47]
	v_cndmask_b32_e64 v135, 0, v135, s[46:47]
	v_cvt_pk_bf16_f32 v124, v124, v125
	v_cvt_pk_bf16_f32 v125, v126, v127
	v_mov_b32_e32 v126, 0
	v_mov_b32_e32 v127, 0
	v_cvt_pk_bf16_f32 v128, v128, v129
	v_cvt_pk_bf16_f32 v129, v130, v131
	v_cvt_pk_bf16_f32 v130, v132, v133
	v_cvt_pk_bf16_f32 v131, v134, v135
	s_waitcnt lgkmcnt(0)
	s_nop 1
	v_mfma_f32_16x16x32_bf16 v[136:139], v[124:127], v[212:215], v[136:139]
	v_mfma_f32_16x16x32_bf16 v[140:143], v[128:131], v[212:215], v[140:143]
	ds_read_b128 v[220:223], v9 offset:17408
	ds_read_b128 v[228:231], v10 offset:37888
	ds_read_b128 v[224:227], v9 offset:18688
	ds_read_b128 v[232:235], v10 offset:37952
	s_waitcnt lgkmcnt(2)
	v_pk_mul_f32 v[92:93], v[92:93], v[228:229]
	v_pk_mul_f32 v[94:95], v[94:95], v[230:231]
	s_nop 1
	v_mfma_f32_16x16x32_bf16 v[92:95], v[220:223], v[216:219], v[92:95]
	ds_read_b128 v[220:223], v9 offset:19968
	ds_read_b128 v[228:231], v10 offset:38016
	s_waitcnt lgkmcnt(2)
	v_pk_mul_f32 v[96:97], v[96:97], v[232:233]
	v_pk_mul_f32 v[98:99], v[98:99], v[234:235]
	s_nop 1
	v_mfma_f32_16x16x32_bf16 v[96:99], v[224:227], v[216:219], v[96:99]
	ds_read_b128 v[224:227], v9 offset:21248
	ds_read_b128 v[232:235], v10 offset:38080
	s_waitcnt lgkmcnt(2)
	v_pk_mul_f32 v[100:101], v[100:101], v[228:229]
	v_pk_mul_f32 v[102:103], v[102:103], v[230:231]
	s_nop 1
	v_mfma_f32_16x16x32_bf16 v[100:103], v[220:223], v[216:219], v[100:103]
	ds_read_b128 v[220:223], v9 offset:22528
	ds_read_b128 v[228:231], v10 offset:38144
	s_waitcnt lgkmcnt(2)
	v_pk_mul_f32 v[104:105], v[104:105], v[232:233]
	v_pk_mul_f32 v[106:107], v[106:107], v[234:235]
	s_nop 1
	v_mfma_f32_16x16x32_bf16 v[104:107], v[224:227], v[216:219], v[104:107]
	ds_read_b128 v[224:227], v9 offset:23808
	ds_read_b128 v[232:235], v10 offset:38208
	s_waitcnt lgkmcnt(2)
	v_pk_mul_f32 v[108:109], v[108:109], v[228:229]
	v_pk_mul_f32 v[110:111], v[110:111], v[230:231]
	s_nop 1
	v_mfma_f32_16x16x32_bf16 v[108:111], v[220:223], v[216:219], v[108:111]
	ds_read_b128 v[220:223], v9 offset:25088
	ds_read_b128 v[228:231], v10 offset:38272
	s_waitcnt lgkmcnt(2)
	v_pk_mul_f32 v[112:113], v[112:113], v[232:233]
	v_pk_mul_f32 v[114:115], v[114:115], v[234:235]
	s_nop 1
	v_mfma_f32_16x16x32_bf16 v[112:115], v[224:227], v[216:219], v[112:115]
	ds_read_b128 v[224:227], v9 offset:26368
	ds_read_b128 v[232:235], v10 offset:38336
	s_waitcnt lgkmcnt(2)
	v_pk_mul_f32 v[116:117], v[116:117], v[228:229]
	v_pk_mul_f32 v[118:119], v[118:119], v[230:231]
	s_nop 1
	v_mfma_f32_16x16x32_bf16 v[116:119], v[220:223], v[216:219], v[116:119]
	s_waitcnt lgkmcnt(0)
	v_pk_mul_f32 v[120:121], v[120:121], v[232:233]
	v_pk_mul_f32 v[122:123], v[122:123], v[234:235]
	s_nop 1
	v_mfma_f32_16x16x32_bf16 v[120:123], v[224:227], v[216:219], v[120:123]
	ds_write_b32 v11, v136
	ds_write_b32 v11, v140 offset:8448
	ds_write_b32 v11, v137 offset:528
	ds_write_b32 v11, v141 offset:8976
	ds_write_b32 v11, v138 offset:1056
	ds_write_b32 v11, v142 offset:9504
	ds_write_b32 v11, v139 offset:1584
	ds_write_b32 v11, v143 offset:10032
	ds_read_b32 v200, v0 offset:55296
	ds_read_b32 v201, v0 offset:55808
	ds_read_b32 v202, v0 offset:56320
	ds_read_b32 v203, v0 offset:56832
	v_lshl_or_b32 v220, v53, 16, v52
	v_lshl_or_b32 v221, v55, 16, v54
	v_lshl_or_b32 v222, v57, 16, v56
	v_lshl_or_b32 v223, v59, 16, v58
	ds_write_b128 v4, v[220:223] offset:27648
	s_waitcnt lgkmcnt(1)
	v_mul_f32_e32 v204, v21, v200
	v_fmac_f32_e32 v204, v22, v201
	v_fmac_f32_e32 v204, v23, v202
	v_add_f32_e32 v205, v200, v201
	v_add_f32_e32 v205, v205, v202
	v_add_f32_e32 v205, v205, v203
	v_add_f32_e32 v218, v204, v36
	v_mul_f32_e32 v207, 0x3fb8aa3b, v28
	v_exp_f32_e32 v207, v207
	v_lshlrev_b32_e32 v209, 16, v44
	v_sub_f32_e32 v208, 1.0, v207
	v_mul_f32_e32 v207, 0x3fb8aa3b, v218
	v_exp_f32_e32 v207, v207
	v_add_f32_e32 v206, v218, v24
	v_mul_f32_e32 v224, v209, v207
	v_mul_f32_e32 v206, 0x3fb8aa3b, v206
	v_exp_f32_e32 v206, v206
	v_sub_f32_e32 v207, v205, v218
	v_mul_f32_e32 v28, v209, v206
	v_mul_f32_e32 v207, 0x3fb8aa3b, v207
	v_exp_f32_e32 v207, v207
	v_min_f32_e64 v206, -v218, s29
	v_mul_f32_e32 v210, v208, v207
	v_mul_f32_e32 v206, 0x3fb8aa3b, v206
	v_exp_f32_e32 v206, v206
	s_nop 0
	v_mul_f32_e32 v232, v208, v206
	v_add_f32_e32 v218, v204, v37
	v_mul_f32_e32 v207, 0x3fb8aa3b, v29
	v_exp_f32_e32 v207, v207
	v_lshlrev_b32_e32 v209, 16, v45
	v_sub_f32_e32 v208, 1.0, v207
	v_mul_f32_e32 v207, 0x3fb8aa3b, v218
	v_exp_f32_e32 v207, v207
	v_add_f32_e32 v206, v218, v24
	v_mul_f32_e32 v225, v209, v207
	v_mul_f32_e32 v206, 0x3fb8aa3b, v206
	v_exp_f32_e32 v206, v206
	v_sub_f32_e32 v207, v205, v218
	v_mul_f32_e32 v29, v209, v206
	v_mul_f32_e32 v207, 0x3fb8aa3b, v207
	v_exp_f32_e32 v207, v207
	v_min_f32_e64 v206, -v218, s29
	v_mul_f32_e32 v211, v208, v207
	v_mul_f32_e32 v206, 0x3fb8aa3b, v206
	v_exp_f32_e32 v206, v206
	s_nop 0
	v_mul_f32_e32 v233, v208, v206
	v_add_f32_e32 v218, v204, v38
	v_mul_f32_e32 v207, 0x3fb8aa3b, v30
	v_exp_f32_e32 v207, v207
	v_lshlrev_b32_e32 v209, 16, v46
	v_sub_f32_e32 v208, 1.0, v207
	v_mul_f32_e32 v207, 0x3fb8aa3b, v218
	v_exp_f32_e32 v207, v207
	v_add_f32_e32 v206, v218, v24
	v_mul_f32_e32 v226, v209, v207
	v_mul_f32_e32 v206, 0x3fb8aa3b, v206
	v_exp_f32_e32 v206, v206
	v_sub_f32_e32 v207, v205, v218
	v_mul_f32_e32 v30, v209, v206
	v_mul_f32_e32 v207, 0x3fb8aa3b, v207
	v_exp_f32_e32 v207, v207
	v_min_f32_e64 v206, -v218, s29
	v_mul_f32_e32 v212, v208, v207
	v_mul_f32_e32 v206, 0x3fb8aa3b, v206
	v_exp_f32_e32 v206, v206
	s_nop 0
	v_mul_f32_e32 v234, v208, v206
	v_add_f32_e32 v218, v204, v39
	v_mul_f32_e32 v207, 0x3fb8aa3b, v31
	v_exp_f32_e32 v207, v207
	v_lshlrev_b32_e32 v209, 16, v47
	v_sub_f32_e32 v208, 1.0, v207
	v_mul_f32_e32 v207, 0x3fb8aa3b, v218
	v_exp_f32_e32 v207, v207
	v_add_f32_e32 v206, v218, v24
	v_mul_f32_e32 v227, v209, v207
	v_mul_f32_e32 v206, 0x3fb8aa3b, v206
	v_exp_f32_e32 v206, v206
	v_sub_f32_e32 v207, v205, v218
	v_mul_f32_e32 v31, v209, v206
	v_mul_f32_e32 v207, 0x3fb8aa3b, v207
	v_exp_f32_e32 v207, v207
	v_min_f32_e64 v206, -v218, s29
	v_mul_f32_e32 v213, v208, v207
	v_mul_f32_e32 v206, 0x3fb8aa3b, v206
	v_exp_f32_e32 v206, v206
	s_nop 0
	v_mul_f32_e32 v235, v208, v206
	v_add_f32_e32 v218, v204, v40
	v_mul_f32_e32 v207, 0x3fb8aa3b, v32
	v_exp_f32_e32 v207, v207
	v_lshlrev_b32_e32 v209, 16, v48
	v_sub_f32_e32 v208, 1.0, v207
	v_mul_f32_e32 v207, 0x3fb8aa3b, v218
	v_exp_f32_e32 v207, v207
	v_add_f32_e32 v206, v218, v24
	v_mul_f32_e32 v228, v209, v207
	v_mul_f32_e32 v206, 0x3fb8aa3b, v206
	v_exp_f32_e32 v206, v206
	v_sub_f32_e32 v207, v205, v218
	v_mul_f32_e32 v32, v209, v206
	v_mul_f32_e32 v207, 0x3fb8aa3b, v207
	v_exp_f32_e32 v207, v207
	v_min_f32_e64 v206, -v218, s29
	v_mul_f32_e32 v214, v208, v207
	v_mul_f32_e32 v206, 0x3fb8aa3b, v206
	v_exp_f32_e32 v206, v206
	s_nop 0
	v_mul_f32_e32 v236, v208, v206
	v_add_f32_e32 v218, v204, v41
	v_mul_f32_e32 v207, 0x3fb8aa3b, v33
	v_exp_f32_e32 v207, v207
	v_lshlrev_b32_e32 v209, 16, v49
	v_sub_f32_e32 v208, 1.0, v207
	v_mul_f32_e32 v207, 0x3fb8aa3b, v218
	v_exp_f32_e32 v207, v207
	v_add_f32_e32 v206, v218, v24
	v_mul_f32_e32 v229, v209, v207
	v_mul_f32_e32 v206, 0x3fb8aa3b, v206
	v_exp_f32_e32 v206, v206
	v_sub_f32_e32 v207, v205, v218
	v_mul_f32_e32 v33, v209, v206
	v_mul_f32_e32 v207, 0x3fb8aa3b, v207
	v_exp_f32_e32 v207, v207
	v_min_f32_e64 v206, -v218, s29
	v_mul_f32_e32 v215, v208, v207
	v_mul_f32_e32 v206, 0x3fb8aa3b, v206
	v_exp_f32_e32 v206, v206
	s_nop 0
	v_mul_f32_e32 v237, v208, v206
	v_add_f32_e32 v218, v204, v42
	v_mul_f32_e32 v207, 0x3fb8aa3b, v34
	v_exp_f32_e32 v207, v207
	v_lshlrev_b32_e32 v209, 16, v50
	v_sub_f32_e32 v208, 1.0, v207
	v_mul_f32_e32 v207, 0x3fb8aa3b, v218
	v_exp_f32_e32 v207, v207
	v_add_f32_e32 v206, v218, v24
	v_mul_f32_e32 v230, v209, v207
	v_mul_f32_e32 v206, 0x3fb8aa3b, v206
	v_exp_f32_e32 v206, v206
	v_sub_f32_e32 v207, v205, v218
	v_mul_f32_e32 v34, v209, v206
	v_mul_f32_e32 v207, 0x3fb8aa3b, v207
	v_exp_f32_e32 v207, v207
	v_min_f32_e64 v206, -v218, s29
	v_mul_f32_e32 v216, v208, v207
	v_mul_f32_e32 v206, 0x3fb8aa3b, v206
	v_exp_f32_e32 v206, v206
	s_nop 0
	v_mul_f32_e32 v238, v208, v206
	v_add_f32_e32 v218, v204, v43
	v_mul_f32_e32 v207, 0x3fb8aa3b, v35
	v_exp_f32_e32 v207, v207
	v_lshlrev_b32_e32 v209, 16, v51
	v_sub_f32_e32 v208, 1.0, v207
	v_mul_f32_e32 v207, 0x3fb8aa3b, v218
	v_exp_f32_e32 v207, v207
	v_add_f32_e32 v206, v218, v24
	v_mul_f32_e32 v231, v209, v207
	v_mul_f32_e32 v206, 0x3fb8aa3b, v206
	v_exp_f32_e32 v206, v206
	v_sub_f32_e32 v207, v205, v218
	v_mul_f32_e32 v35, v209, v206
	v_mul_f32_e32 v207, 0x3fb8aa3b, v207
	v_exp_f32_e32 v207, v207
	v_min_f32_e64 v206, -v218, s29
	v_mul_f32_e32 v217, v208, v207
	v_mul_f32_e32 v206, 0x3fb8aa3b, v206
	v_exp_f32_e32 v206, v206
	s_nop 0
	v_mul_f32_e32 v239, v208, v206
	v_cvt_pk_bf16_f32 v224, v224, v225
	ds_write_b16 v2, v224
	ds_write_b16_d16_hi v2, v224 offset:272
	v_cvt_pk_bf16_f32 v232, v232, v233
	ds_write_b16 v2, v232 offset:8704
	ds_write_b16_d16_hi v2, v232 offset:8976
	v_cvt_pk_bf16_f32 v226, v226, v227
	ds_write_b16 v2, v226 offset:544
	ds_write_b16_d16_hi v2, v226 offset:816
	v_cvt_pk_bf16_f32 v234, v234, v235
	ds_write_b16 v2, v234 offset:9248
	ds_write_b16_d16_hi v2, v234 offset:9520
	v_cvt_pk_bf16_f32 v228, v228, v229
	ds_write_b16 v2, v228 offset:1088
	ds_write_b16_d16_hi v2, v228 offset:1360
	v_cvt_pk_bf16_f32 v236, v236, v237
	ds_write_b16 v2, v236 offset:9792
	ds_write_b16_d16_hi v2, v236 offset:10064
	v_cvt_pk_bf16_f32 v230, v230, v231
	ds_write_b16 v2, v230 offset:1632
	ds_write_b16_d16_hi v2, v230 offset:1904
	v_cvt_pk_bf16_f32 v238, v238, v239
	ds_write_b16 v2, v238 offset:10336
	ds_write_b16_d16_hi v2, v238 offset:10608
	v_cvt_pk_bf16_f32 v210, v210, v211
	v_cvt_pk_bf16_f32 v211, v212, v213
	v_cvt_pk_bf16_f32 v212, v214, v215
	v_cvt_pk_bf16_f32 v213, v216, v217
	ds_write_b128 v4, v[210:213] offset:17408
	v_cvt_pk_bf16_f32 v28, v28, v29
	v_cvt_pk_bf16_f32 v30, v30, v31
	v_cvt_pk_bf16_f32 v32, v32, v33
	v_cvt_pk_bf16_f32 v34, v34, v35
	global_store_short v18, v28, s[12:13]
	global_store_short_d16_hi v18, v28, s[12:13] offset:1536
	global_store_short v18, v30, s[12:13] offset:3072
	global_store_short_d16_hi v19, v30, s[12:13]
	global_store_short v19, v32, s[12:13] offset:1536
	global_store_short_d16_hi v19, v32, s[12:13] offset:3072
	global_store_short v20, v34, s[12:13]
	global_store_short_d16_hi v20, v34, s[12:13] offset:1536
	s_add_u32 s12, s12, 0xc000
	s_addc_u32 s13, s13, 0
	s_cmp_gt_u32 s18, 1
	s_cbranch_scc1 .Lhg_w01_10
	v_mul_f32_e32 v207, 0x3fb8aa3b, v205
	v_exp_f32_e32 v207, v207
	s_nop 0
	ds_write_b32 v26, v207 offset:37888

.Lhg_bfirst_8:
	ds_read_b32 v200, v0 offset:55296
	ds_read_b32 v201, v0 offset:55808
	ds_read_b32 v202, v0 offset:56320
	ds_read_b32 v203, v0 offset:56832
	v_lshl_or_b32 v220, v53, 16, v52
	v_lshl_or_b32 v221, v55, 16, v54
	v_lshl_or_b32 v222, v57, 16, v56
	v_lshl_or_b32 v223, v59, 16, v58
	ds_write_b128 v4, v[220:223] offset:27648
	s_waitcnt lgkmcnt(1)
	v_mul_f32_e32 v204, v21, v200
	v_fmac_f32_e32 v204, v22, v201
	v_fmac_f32_e32 v204, v23, v202
	v_add_f32_e32 v205, v200, v201
	v_add_f32_e32 v205, v205, v202
	v_add_f32_e32 v205, v205, v203
	v_add_f32_e32 v218, v204, v36
	v_mul_f32_e32 v207, 0x3fb8aa3b, v28
	v_exp_f32_e32 v207, v207
	v_lshlrev_b32_e32 v209, 16, v44
	v_sub_f32_e32 v208, 1.0, v207
	v_mul_f32_e32 v207, 0x3fb8aa3b, v218
	v_exp_f32_e32 v207, v207
	v_add_f32_e32 v206, v218, v24
	v_mul_f32_e32 v224, v209, v207
	v_mul_f32_e32 v206, 0x3fb8aa3b, v206
	v_exp_f32_e32 v206, v206
	v_sub_f32_e32 v207, v205, v218
	v_mul_f32_e32 v28, v209, v206
	v_mul_f32_e32 v207, 0x3fb8aa3b, v207
	v_exp_f32_e32 v207, v207
	v_min_f32_e64 v206, -v218, s29
	v_mul_f32_e32 v210, v208, v207
	v_mul_f32_e32 v206, 0x3fb8aa3b, v206
	v_exp_f32_e32 v206, v206
	s_nop 0
	v_mul_f32_e32 v232, v208, v206
	v_add_f32_e32 v218, v204, v37
	v_mul_f32_e32 v207, 0x3fb8aa3b, v29
	v_exp_f32_e32 v207, v207
	v_lshlrev_b32_e32 v209, 16, v45
	v_sub_f32_e32 v208, 1.0, v207
	v_mul_f32_e32 v207, 0x3fb8aa3b, v218
	v_exp_f32_e32 v207, v207
	v_add_f32_e32 v206, v218, v24
	v_mul_f32_e32 v225, v209, v207
	v_mul_f32_e32 v206, 0x3fb8aa3b, v206
	v_exp_f32_e32 v206, v206
	v_sub_f32_e32 v207, v205, v218
	v_mul_f32_e32 v29, v209, v206
	v_mul_f32_e32 v207, 0x3fb8aa3b, v207
	v_exp_f32_e32 v207, v207
	v_min_f32_e64 v206, -v218, s29
	v_mul_f32_e32 v211, v208, v207
	v_mul_f32_e32 v206, 0x3fb8aa3b, v206
	v_exp_f32_e32 v206, v206
	s_nop 0
	v_mul_f32_e32 v233, v208, v206
	v_add_f32_e32 v218, v204, v38
	v_mul_f32_e32 v207, 0x3fb8aa3b, v30
	v_exp_f32_e32 v207, v207
	v_lshlrev_b32_e32 v209, 16, v46
	v_sub_f32_e32 v208, 1.0, v207
	v_mul_f32_e32 v207, 0x3fb8aa3b, v218
	v_exp_f32_e32 v207, v207
	v_add_f32_e32 v206, v218, v24
	v_mul_f32_e32 v226, v209, v207
	v_mul_f32_e32 v206, 0x3fb8aa3b, v206
	v_exp_f32_e32 v206, v206
	v_sub_f32_e32 v207, v205, v218
	v_mul_f32_e32 v30, v209, v206
	v_mul_f32_e32 v207, 0x3fb8aa3b, v207
	v_exp_f32_e32 v207, v207
	v_min_f32_e64 v206, -v218, s29
	v_mul_f32_e32 v212, v208, v207
	v_mul_f32_e32 v206, 0x3fb8aa3b, v206
	v_exp_f32_e32 v206, v206
	s_nop 0
	v_mul_f32_e32 v234, v208, v206
	v_add_f32_e32 v218, v204, v39
	v_mul_f32_e32 v207, 0x3fb8aa3b, v31
	v_exp_f32_e32 v207, v207
	v_lshlrev_b32_e32 v209, 16, v47
	v_sub_f32_e32 v208, 1.0, v207
	v_mul_f32_e32 v207, 0x3fb8aa3b, v218
	v_exp_f32_e32 v207, v207
	v_add_f32_e32 v206, v218, v24
	v_mul_f32_e32 v227, v209, v207
	v_mul_f32_e32 v206, 0x3fb8aa3b, v206
	v_exp_f32_e32 v206, v206
	v_sub_f32_e32 v207, v205, v218
	v_mul_f32_e32 v31, v209, v206
	v_mul_f32_e32 v207, 0x3fb8aa3b, v207
	v_exp_f32_e32 v207, v207
	v_min_f32_e64 v206, -v218, s29
	v_mul_f32_e32 v213, v208, v207
	v_mul_f32_e32 v206, 0x3fb8aa3b, v206
	v_exp_f32_e32 v206, v206
	s_nop 0
	v_mul_f32_e32 v235, v208, v206
	v_add_f32_e32 v218, v204, v40
	v_mul_f32_e32 v207, 0x3fb8aa3b, v32
	v_exp_f32_e32 v207, v207
	v_lshlrev_b32_e32 v209, 16, v48
	v_sub_f32_e32 v208, 1.0, v207
	v_mul_f32_e32 v207, 0x3fb8aa3b, v218
	v_exp_f32_e32 v207, v207
	v_add_f32_e32 v206, v218, v24
	v_mul_f32_e32 v228, v209, v207
	v_mul_f32_e32 v206, 0x3fb8aa3b, v206
	v_exp_f32_e32 v206, v206
	v_sub_f32_e32 v207, v205, v218
	v_mul_f32_e32 v32, v209, v206
	v_mul_f32_e32 v207, 0x3fb8aa3b, v207
	v_exp_f32_e32 v207, v207
	v_min_f32_e64 v206, -v218, s29
	v_mul_f32_e32 v214, v208, v207
	v_mul_f32_e32 v206, 0x3fb8aa3b, v206
	v_exp_f32_e32 v206, v206
	s_nop 0
	v_mul_f32_e32 v236, v208, v206
	v_add_f32_e32 v218, v204, v41
	v_mul_f32_e32 v207, 0x3fb8aa3b, v33
	v_exp_f32_e32 v207, v207
	v_lshlrev_b32_e32 v209, 16, v49
	v_sub_f32_e32 v208, 1.0, v207
	v_mul_f32_e32 v207, 0x3fb8aa3b, v218
	v_exp_f32_e32 v207, v207
	v_add_f32_e32 v206, v218, v24
	v_mul_f32_e32 v229, v209, v207
	v_mul_f32_e32 v206, 0x3fb8aa3b, v206
	v_exp_f32_e32 v206, v206
	v_sub_f32_e32 v207, v205, v218
	v_mul_f32_e32 v33, v209, v206
	v_mul_f32_e32 v207, 0x3fb8aa3b, v207
	v_exp_f32_e32 v207, v207
	v_min_f32_e64 v206, -v218, s29
	v_mul_f32_e32 v215, v208, v207
	v_mul_f32_e32 v206, 0x3fb8aa3b, v206
	v_exp_f32_e32 v206, v206
	s_nop 0
	v_mul_f32_e32 v237, v208, v206
	v_add_f32_e32 v218, v204, v42
	v_mul_f32_e32 v207, 0x3fb8aa3b, v34
	v_exp_f32_e32 v207, v207
	v_lshlrev_b32_e32 v209, 16, v50
	v_sub_f32_e32 v208, 1.0, v207
	v_mul_f32_e32 v207, 0x3fb8aa3b, v218
	v_exp_f32_e32 v207, v207
	v_add_f32_e32 v206, v218, v24
	v_mul_f32_e32 v230, v209, v207
	v_mul_f32_e32 v206, 0x3fb8aa3b, v206
	v_exp_f32_e32 v206, v206
	v_sub_f32_e32 v207, v205, v218
	v_mul_f32_e32 v34, v209, v206
	v_mul_f32_e32 v207, 0x3fb8aa3b, v207
	v_exp_f32_e32 v207, v207
	v_min_f32_e64 v206, -v218, s29
	v_mul_f32_e32 v216, v208, v207
	v_mul_f32_e32 v206, 0x3fb8aa3b, v206
	v_exp_f32_e32 v206, v206
	s_nop 0
	v_mul_f32_e32 v238, v208, v206
	v_add_f32_e32 v218, v204, v43
	v_mul_f32_e32 v207, 0x3fb8aa3b, v35
	v_exp_f32_e32 v207, v207
	v_lshlrev_b32_e32 v209, 16, v51
	v_sub_f32_e32 v208, 1.0, v207
	v_mul_f32_e32 v207, 0x3fb8aa3b, v218
	v_exp_f32_e32 v207, v207
	v_add_f32_e32 v206, v218, v24
	v_mul_f32_e32 v231, v209, v207
	v_mul_f32_e32 v206, 0x3fb8aa3b, v206
	v_exp_f32_e32 v206, v206
	v_sub_f32_e32 v207, v205, v218
	v_mul_f32_e32 v35, v209, v206
	v_mul_f32_e32 v207, 0x3fb8aa3b, v207
	v_exp_f32_e32 v207, v207
	v_min_f32_e64 v206, -v218, s29
	v_mul_f32_e32 v217, v208, v207
	v_mul_f32_e32 v206, 0x3fb8aa3b, v206
	v_exp_f32_e32 v206, v206
	s_nop 0
	v_mul_f32_e32 v239, v208, v206
	v_cvt_pk_bf16_f32 v224, v224, v225
	ds_write_b16 v2, v224
	ds_write_b16_d16_hi v2, v224 offset:272
	v_cvt_pk_bf16_f32 v232, v232, v233
	ds_write_b16 v2, v232 offset:8704
	ds_write_b16_d16_hi v2, v232 offset:8976
	v_cvt_pk_bf16_f32 v226, v226, v227
	ds_write_b16 v2, v226 offset:544
	ds_write_b16_d16_hi v2, v226 offset:816
	v_cvt_pk_bf16_f32 v234, v234, v235
	ds_write_b16 v2, v234 offset:9248
	ds_write_b16_d16_hi v2, v234 offset:9520
	v_cvt_pk_bf16_f32 v228, v228, v229
	ds_write_b16 v2, v228 offset:1088
	ds_write_b16_d16_hi v2, v228 offset:1360
	v_cvt_pk_bf16_f32 v236, v236, v237
	ds_write_b16 v2, v236 offset:9792
	ds_write_b16_d16_hi v2, v236 offset:10064
	v_cvt_pk_bf16_f32 v230, v230, v231
	ds_write_b16 v2, v230 offset:1632
	ds_write_b16_d16_hi v2, v230 offset:1904
	v_cvt_pk_bf16_f32 v238, v238, v239
	ds_write_b16 v2, v238 offset:10336
	ds_write_b16_d16_hi v2, v238 offset:10608
	v_cvt_pk_bf16_f32 v210, v210, v211
	v_cvt_pk_bf16_f32 v211, v212, v213
	v_cvt_pk_bf16_f32 v212, v214, v215
	v_cvt_pk_bf16_f32 v213, v216, v217
	ds_write_b128 v4, v[210:213] offset:17408
	v_cvt_pk_bf16_f32 v28, v28, v29
	v_cvt_pk_bf16_f32 v30, v30, v31
	v_cvt_pk_bf16_f32 v32, v32, v33
	v_cvt_pk_bf16_f32 v34, v34, v35
	global_store_short v18, v28, s[12:13]
	global_store_short_d16_hi v18, v28, s[12:13] offset:1536
	global_store_short v18, v30, s[12:13] offset:3072
	global_store_short_d16_hi v19, v30, s[12:13]
	global_store_short v19, v32, s[12:13] offset:1536
	global_store_short_d16_hi v19, v32, s[12:13] offset:3072
	global_store_short v20, v34, s[12:13]
	global_store_short_d16_hi v20, v34, s[12:13] offset:1536
	s_add_u32 s12, s12, 0xc000
	s_addc_u32 s13, s13, 0
	s_cmp_gt_u32 s18, 1
	s_cbranch_scc1 .Lhg_w01_11
	v_mul_f32_e32 v207, 0x3fb8aa3b, v205
	v_exp_f32_e32 v207, v207
	s_nop 0
	ds_write_b32 v26, v207 offset:37888

.Lhg_joined_9:
	s_waitcnt vmcnt(0) lgkmcnt(0)
	s_barrier
	ds_read_b128 v[200:203], v12
	ds_read_b128 v[204:207], v12 offset:16
	s_waitcnt lgkmcnt(0)
	v_cvt_pk_bf16_f32 v200, v200, v201
	v_cvt_pk_bf16_f32 v201, v202, v203
	v_cvt_pk_bf16_f32 v202, v204, v205
	v_cvt_pk_bf16_f32 v203, v206, v207
	global_store_dwordx4 v13, v[200:203], s[14:15]
	s_add_u32 s14, s14, 0x10000
	s_addc_u32 s15, s15, 0
	v_xor_b32_e32 v2, 0x10000, v2
	v_xor_b32_e32 v4, 0x10000, v4
	v_xor_b32_e32 v26, 0x10000, v26
	v_xor_b32_e32 v5, 0x10000, v5
	v_xor_b32_e32 v6, 0x10000, v6
	v_xor_b32_e32 v7, 0x10000, v7
	v_xor_b32_e32 v8, 0x10000, v8
	v_xor_b32_e32 v9, 0x10000, v9
	v_xor_b32_e32 v10, 0x10000, v10
	s_add_i32 s28, s28, 1
	s_branch .Lhg_loop
.Lhg_last:
	ds_read_b128 v[144:147], v5 offset:8704
	ds_read_b128 v[148:151], v5 offset:13056
	ds_read_b128 v[152:155], v5 offset:0
	ds_read_b128 v[172:175], v5 offset:4352
	ds_read_b128 v[176:179], v5 offset:8768
	ds_read_b128 v[180:183], v5 offset:13120
	ds_read_b128 v[184:187], v5 offset:64
	ds_read_b128 v[188:191], v5 offset:4416
	s_waitcnt lgkmcnt(4)
	v_mfma_f32_16x16x32_bf16 v[124:127], v[144:147], v[152:155], 0
	v_mfma_f32_16x16x32_bf16 v[128:131], v[144:147], v[172:175], 0
	v_mfma_f32_16x16x32_bf16 v[132:135], v[148:151], v[172:175], 0
	ds_read_b128 v[144:147], v5 offset:8832
	ds_read_b128 v[148:151], v5 offset:13184
	ds_read_b128 v[152:155], v5 offset:128
	ds_read_b128 v[172:175], v5 offset:4480
	s_waitcnt lgkmcnt(4)
	v_mfma_f32_16x16x32_bf16 v[124:127], v[176:179], v[184:187], v[124:127]
	v_mfma_f32_16x16x32_bf16 v[128:131], v[176:179], v[188:191], v[128:131]
	v_mfma_f32_16x16x32_bf16 v[132:135], v[180:183], v[188:191], v[132:135]
	ds_read_b128 v[176:179], v5 offset:8896
	ds_read_b128 v[180:183], v5 offset:13248
	ds_read_b128 v[184:187], v5 offset:192
	ds_read_b128 v[188:191], v5 offset:4544
	s_waitcnt lgkmcnt(4)
	v_mfma_f32_16x16x32_bf16 v[124:127], v[144:147], v[152:155], v[124:127]
	v_mfma_f32_16x16x32_bf16 v[128:131], v[144:147], v[172:175], v[128:131]
	v_mfma_f32_16x16x32_bf16 v[132:135], v[148:151], v[172:175], v[132:135]
	s_waitcnt lgkmcnt(0)
	v_mfma_f32_16x16x32_bf16 v[124:127], v[176:179], v[184:187], v[124:127]
	v_mfma_f32_16x16x32_bf16 v[128:131], v[176:179], v[188:191], v[128:131]
	v_mfma_f32_16x16x32_bf16 v[132:135], v[180:183], v[188:191], v[132:135]
	ds_read_b64 v[204:205], v6
	ds_read_b64 v[206:207], v6 offset:32
	ds_read_b64 v[208:209], v6 offset:4352
	ds_read_b64 v[210:211], v6 offset:4384
	v_cvt_pk_bf16_f32 v200, v92, v93
	v_cvt_pk_bf16_f32 v201, v94, v95
	v_cvt_pk_bf16_f32 v202, v96, v97
	v_cvt_pk_bf16_f32 v203, v98, v99
	s_waitcnt lgkmcnt(0)
	s_nop 1
	v_mfma_f32_16x16x32_bf16 v[136:139], v[204:207], v[200:203], 0
	v_mfma_f32_16x16x32_bf16 v[140:143], v[208:211], v[200:203], 0
	ds_read_b64 v[204:205], v6 offset:64
	ds_read_b64 v[206:207], v6 offset:96
	ds_read_b64 v[208:209], v6 offset:4416
	ds_read_b64 v[210:211], v6 offset:4448
	v_cvt_pk_bf16_f32 v200, v100, v101
	v_cvt_pk_bf16_f32 v201, v102, v103
	v_cvt_pk_bf16_f32 v202, v104, v105
	v_cvt_pk_bf16_f32 v203, v106, v107
	s_waitcnt lgkmcnt(0)
	s_nop 1
	v_mfma_f32_16x16x32_bf16 v[136:139], v[204:207], v[200:203], v[136:139]
	v_mfma_f32_16x16x32_bf16 v[140:143], v[208:211], v[200:203], v[140:143]
	ds_read_b64 v[204:205], v6 offset:128
	ds_read_b64 v[206:207], v6 offset:160
	ds_read_b64 v[208:209], v6 offset:4480
	ds_read_b64 v[210:211], v6 offset:4512
	v_cvt_pk_bf16_f32 v200, v108, v109
	v_cvt_pk_bf16_f32 v201, v110, v111
	v_cvt_pk_bf16_f32 v202, v112, v113
	v_cvt_pk_bf16_f32 v203, v114, v115
	s_waitcnt lgkmcnt(0)
	s_nop 1
	v_mfma_f32_16x16x32_bf16 v[136:139], v[204:207], v[200:203], v[136:139]
	v_mfma_f32_16x16x32_bf16 v[140:143], v[208:211], v[200:203], v[140:143]
	ds_read_b64 v[204:205], v6 offset:192
	ds_read_b64 v[206:207], v6 offset:224
	ds_read_b64 v[208:209], v6 offset:4544
	ds_read_b64 v[210:211], v6 offset:4576
	v_cvt_pk_bf16_f32 v200, v116, v117
	v_cvt_pk_bf16_f32 v201, v118, v119
	v_cvt_pk_bf16_f32 v202, v120, v121
	v_cvt_pk_bf16_f32 v203, v122, v123
	s_waitcnt lgkmcnt(0)
	s_nop 1
	v_mfma_f32_16x16x32_bf16 v[136:139], v[204:207], v[200:203], v[136:139]
	v_mfma_f32_16x16x32_bf16 v[140:143], v[208:211], v[200:203], v[140:143]
	ds_read_b64 v[212:213], v7 offset:27648
	ds_read_b64 v[214:215], v7 offset:27680
	ds_read_b128 v[216:219], v8 offset:27648
	v_cndmask_b32_e64 v124, 0, v124, s[40:41]
	v_cndmask_b32_e64 v132, 0, v132, s[40:41]
	v_cndmask_b32_e64 v125, 0, v125, s[42:43]
	v_cndmask_b32_e64 v133, 0, v133, s[42:43]
	v_cndmask_b32_e64 v126, 0, v126, s[44:45]
	v_cndmask_b32_e64 v134, 0, v134, s[44:45]
	v_cndmask_b32_e64 v127, 0, v127, s[46:47]
	v_cndmask_b32_e64 v135, 0, v135, s[46:47]
	v_cvt_pk_bf16_f32 v124, v124, v125
	v_cvt_pk_bf16_f32 v125, v126, v127
	v_mov_b32_e32 v126, 0
	v_mov_b32_e32 v127, 0
	v_cvt_pk_bf16_f32 v128, v128, v129
	v_cvt_pk_bf16_f32 v129, v130, v131
	v_cvt_pk_bf16_f32 v130, v132, v133
	v_cvt_pk_bf16_f32 v131, v134, v135
	s_waitcnt lgkmcnt(0)
	s_nop 1
	v_mfma_f32_16x16x32_bf16 v[136:139], v[124:127], v[212:215], v[136:139]
	v_mfma_f32_16x16x32_bf16 v[140:143], v[128:131], v[212:215], v[140:143]
	ds_read_b128 v[220:223], v9 offset:17408
	ds_read_b128 v[228:231], v10 offset:37888
	ds_read_b128 v[224:227], v9 offset:18688
	ds_read_b128 v[232:235], v10 offset:37952
	s_waitcnt lgkmcnt(2)
	v_pk_mul_f32 v[92:93], v[92:93], v[228:229]
	v_pk_mul_f32 v[94:95], v[94:95], v[230:231]
	s_nop 1
	v_mfma_f32_16x16x32_bf16 v[92:95], v[220:223], v[216:219], v[92:95]
	ds_read_b128 v[220:223], v9 offset:19968
	ds_read_b128 v[228:231], v10 offset:38016
	s_waitcnt lgkmcnt(2)
	v_pk_mul_f32 v[96:97], v[96:97], v[232:233]
	v_pk_mul_f32 v[98:99], v[98:99], v[234:235]
	s_nop 1
	v_mfma_f32_16x16x32_bf16 v[96:99], v[224:227], v[216:219], v[96:99]
	ds_read_b128 v[224:227], v9 offset:21248
	ds_read_b128 v[232:235], v10 offset:38080
	s_waitcnt lgkmcnt(2)
	v_pk_mul_f32 v[100:101], v[100:101], v[228:229]
	v_pk_mul_f32 v[102:103], v[102:103], v[230:231]
	s_nop 1
	v_mfma_f32_16x16x32_bf16 v[100:103], v[220:223], v[216:219], v[100:103]
	ds_read_b128 v[220:223], v9 offset:22528
	ds_read_b128 v[228:231], v10 offset:38144
	s_waitcnt lgkmcnt(2)
	v_pk_mul_f32 v[104:105], v[104:105], v[232:233]
	v_pk_mul_f32 v[106:107], v[106:107], v[234:235]
	s_nop 1
	v_mfma_f32_16x16x32_bf16 v[104:107], v[224:227], v[216:219], v[104:107]
	ds_read_b128 v[224:227], v9 offset:23808
	ds_read_b128 v[232:235], v10 offset:38208
	s_waitcnt lgkmcnt(2)
	v_pk_mul_f32 v[108:109], v[108:109], v[228:229]
	v_pk_mul_f32 v[110:111], v[110:111], v[230:231]
	s_nop 1
	v_mfma_f32_16x16x32_bf16 v[108:111], v[220:223], v[216:219], v[108:111]
	ds_read_b128 v[220:223], v9 offset:25088
	ds_read_b128 v[228:231], v10 offset:38272
	s_waitcnt lgkmcnt(2)
	v_pk_mul_f32 v[112:113], v[112:113], v[232:233]
	v_pk_mul_f32 v[114:115], v[114:115], v[234:235]
	s_nop 1
	v_mfma_f32_16x16x32_bf16 v[112:115], v[224:227], v[216:219], v[112:115]
	ds_read_b128 v[224:227], v9 offset:26368
	ds_read_b128 v[232:235], v10 offset:38336
	s_waitcnt lgkmcnt(2)
	v_pk_mul_f32 v[116:117], v[116:117], v[228:229]
	v_pk_mul_f32 v[118:119], v[118:119], v[230:231]
	s_nop 1
	v_mfma_f32_16x16x32_bf16 v[116:119], v[220:223], v[216:219], v[116:119]
	s_waitcnt lgkmcnt(0)
	v_pk_mul_f32 v[120:121], v[120:121], v[232:233]
	v_pk_mul_f32 v[122:123], v[122:123], v[234:235]
	s_nop 1
	v_mfma_f32_16x16x32_bf16 v[120:123], v[224:227], v[216:219], v[120:123]
	ds_write_b32 v11, v136
	ds_write_b32 v11, v140 offset:8448
	ds_write_b32 v11, v137 offset:528
	ds_write_b32 v11, v141 offset:8976
	ds_write_b32 v11, v138 offset:1056
	ds_write_b32 v11, v142 offset:9504
	ds_write_b32 v11, v139 offset:1584
	ds_write_b32 v11, v143 offset:10032
	s_waitcnt lgkmcnt(0)
	s_barrier
	ds_read_b128 v[200:203], v12
	ds_read_b128 v[204:207], v12 offset:16
	s_waitcnt lgkmcnt(0)
	v_cvt_pk_bf16_f32 v200, v200, v201
	v_cvt_pk_bf16_f32 v201, v202, v203
	v_cvt_pk_bf16_f32 v202, v204, v205
	v_cvt_pk_bf16_f32 v203, v206, v207
	global_store_dwordx4 v13, v[200:203], s[14:15]
	s_add_u32 s14, s14, 0x10000
	s_addc_u32 s15, s15, 0
	s_lshl_b32 s0, s2, 16
	s_add_u32 s4, s6, s0
	s_addc_u32 s5, s7, 0
	s_add_u32 s4, s4, 0x4200000
	s_addc_u32 s5, s5, 0
	global_store_dword v25, v92, s[4:5] offset:0
	global_store_dword v25, v93, s[4:5] offset:512
	global_store_dword v25, v94, s[4:5] offset:1024
	global_store_dword v25, v95, s[4:5] offset:1536
	v_add_u32_e32 v25, 0x2000, v25
	global_store_dword v25, v96, s[4:5] offset:0
	global_store_dword v25, v97, s[4:5] offset:512
	global_store_dword v25, v98, s[4:5] offset:1024
	global_store_dword v25, v99, s[4:5] offset:1536
	v_add_u32_e32 v25, 0x2000, v25
	global_store_dword v25, v100, s[4:5] offset:0
	global_store_dword v25, v101, s[4:5] offset:512
	global_store_dword v25, v102, s[4:5] offset:1024
	global_store_dword v25, v103, s[4:5] offset:1536
	v_add_u32_e32 v25, 0x2000, v25
	global_store_dword v25, v104, s[4:5] offset:0
	global_store_dword v25, v105, s[4:5] offset:512
	global_store_dword v25, v106, s[4:5] offset:1024
	global_store_dword v25, v107, s[4:5] offset:1536
	v_add_u32_e32 v25, 0x2000, v25
	global_store_dword v25, v108, s[4:5] offset:0
	global_store_dword v25, v109, s[4:5] offset:512
	global_store_dword v25, v110, s[4:5] offset:1024
	global_store_dword v25, v111, s[4:5] offset:1536
	v_add_u32_e32 v25, 0x2000, v25
	global_store_dword v25, v112, s[4:5] offset:0
	global_store_dword v25, v113, s[4:5] offset:512
	global_store_dword v25, v114, s[4:5] offset:1024
	global_store_dword v25, v115, s[4:5] offset:1536
	v_add_u32_e32 v25, 0x2000, v25
	global_store_dword v25, v116, s[4:5] offset:0
	global_store_dword v25, v117, s[4:5] offset:512
	global_store_dword v25, v118, s[4:5] offset:1024
	global_store_dword v25, v119, s[4:5] offset:1536
	v_add_u32_e32 v25, 0x2000, v25
	global_store_dword v25, v120, s[4:5] offset:0
	global_store_dword v25, v121, s[4:5] offset:512
	global_store_dword v25, v122, s[4:5] offset:1024
	global_store_dword v25, v123, s[4:5] offset:1536
	s_cmp_gt_u32 s18, 1
	s_cbranch_scc1 .Lhg_done
	v_mul_f32_e32 v200, 0x3fb8aa3b, v24
	v_exp_f32_e32 v200, v200
	s_lshl_b32 s0, s2, 9
	s_add_u32 s4, s6, s0
	s_addc_u32 s5, s7, 0
	s_add_u32 s4, s4, 0x5200000
	s_addc_u32 s5, s5, 0
	global_store_dword v0, v200, s[4:5]
.Lhg_done:
	v_mov_b32_e32 v58, v194
